# attention: third V-tile LDS buffer (V(t) in buffer t mod 3), one s_barrier per key tile instead of two, loop body laid out 3x; output patches moved up 8 KiB
# speedup vs baseline: 1.0059x; 1.0059x over previous
.LBB0_692:
	s_or_b64 exec, exec, s[8:9]
	v_mov_b32_e32 v134, 0
	v_mov_b32_e32 v138, 0
	v_mov_b32_e32 v135, 0
	v_mov_b32_e32 v139, 0
	v_mov_b32_e32 v136, 0
	v_mov_b32_e32 v140, 0
	v_mov_b32_e32 v137, 0
	v_mov_b32_e32 v141, 0
	v_cvt_pk_fp8_f32 v134, v118, v120
	v_cvt_pk_fp8_f32 v138, v132, v133
	v_cvt_pk_fp8_f32 v135, v113, v114
	v_cvt_pk_fp8_f32 v139, v130, v131
	v_cvt_pk_fp8_f32 v136, v108, v110
	v_cvt_pk_fp8_f32 v140, v123, v124
	v_cvt_pk_fp8_f32 v137, v103, v104
	v_cvt_pk_fp8_f32 v141, v121, v122
	v_cvt_pk_fp8_f32 v134, v105, v109 op_sel:[0,0,1]
	v_cvt_pk_fp8_f32 v138, v125, v126 op_sel:[0,0,1]
	v_cvt_pk_fp8_f32 v135, v111, v112 op_sel:[0,0,1]
	v_cvt_pk_fp8_f32 v139, v127, v128 op_sel:[0,0,1]
	v_cvt_pk_fp8_f32 v136, v99, v100 op_sel:[0,0,1]
	v_cvt_pk_fp8_f32 v140, v115, v116 op_sel:[0,0,1]
	v_cvt_pk_fp8_f32 v137, v101, v102 op_sel:[0,0,1]
	v_cvt_pk_fp8_f32 v141, v117, v119 op_sel:[0,0,1]
	s_waitcnt lgkmcnt(0)
	s_ashr_i32 s6, s71, 9
	s_ashr_i32 s7, s6, 31
	s_waitcnt lgkmcnt(6)
	v_mfma_scale_f32_32x32x64_f8f6f4 v[2:17], v[134:141], v[90:97], v[2:17], v1, v1 op_sel_hi:[0,0,0]
	v_add_u32_e32 v90, v183, v184
	s_lshl_b64 s[6:7], s[6:7], 13
	s_or_b32 s6, s6, s55
	s_mulk_i32 s7, 0x1800
	s_mul_hi_u32 s8, s6, 0x1800
	s_add_i32 s8, s8, s7
	s_mulk_i32 s6, 0x1800
	s_add_u32 s6, s50, s6
	s_addc_u32 s7, s51, s8
	s_lshl_b32 s8, s54, 7
	s_and_b32 s8, s8, 0x780
	s_add_u32 s6, s6, s8
	s_addc_u32 s7, s7, 0
	s_add_u32 s6, s6, 0x27701000
	s_addc_u32 s7, s7, 0
	s_waitcnt lgkmcnt(3)
	v_mfma_scale_f32_32x32x64_f8f6f4 v[50:65], v[134:141], v[82:89], v[50:65], v1, v1 op_sel_hi:[0,0,0]
	ds_read_b128 v[82:85], v90 offset:40960
	ds_read_b128 v[86:89], v90 offset:40992
	s_add_i32 s71, s71, s34
	s_cmpk_gt_i32 s71, 0x3ff
	s_waitcnt lgkmcnt(1)
	v_rcp_f32_e32 v82, v82
	v_rcp_f32_e32 v83, v83
	v_rcp_f32_e32 v84, v84
	v_rcp_f32_e32 v85, v85
	v_mul_f32_e32 v2, v2, v82
	s_waitcnt lgkmcnt(0)
	v_rcp_f32_e32 v86, v86
	v_rcp_f32_e32 v87, v87
	v_rcp_f32_e32 v88, v88
	v_rcp_f32_e32 v89, v89
	v_mfma_scale_f32_32x32x64_f8f6f4 v[34:49], v[134:141], v[74:81], v[34:49], v1, v1 op_sel_hi:[0,0,0]
	ds_read_b128 v[74:77], v90 offset:41024
	ds_read_b128 v[78:81], v90 offset:41056
	s_waitcnt lgkmcnt(1)
	v_rcp_f32_e32 v74, v74
	v_rcp_f32_e32 v75, v75
	v_rcp_f32_e32 v76, v76
	v_rcp_f32_e32 v77, v77
	s_waitcnt lgkmcnt(0)
	v_rcp_f32_e32 v78, v78
	v_mfma_scale_f32_32x32x64_f8f6f4 v[18:33], v[134:141], v[66:73], v[18:33], v1, v1 op_sel_hi:[0,0,0]
	v_mul_lo_u32 v69, v181, s67
	v_add_u32_e32 v69, 0, v69
	v_lshlrev_b32_e32 v70, 1, v180
	v_mul_u32_u24_e32 v71, 0x440, v182
	v_add3_u32 v70, v69, v70, v71
	v_bfe_u32 v71, v2, 16, 1
	v_add3_u32 v2, v2, v71, s68
	ds_write_b16_d16_hi v70, v2 offset:53248
	v_mul_f32_e32 v2, v50, v82
	v_bfe_u32 v50, v2, 16, 1
	v_add3_u32 v2, v2, v50, s68
	ds_write_b16_d16_hi v70, v2 offset:53312
	v_mul_f32_e32 v2, v34, v82
	v_bfe_u32 v34, v2, 16, 1
	v_add3_u32 v2, v2, v34, s68
	ds_write_b16_d16_hi v70, v2 offset:53376
	s_nop 3
	v_mul_f32_e32 v2, v18, v82
	v_bfe_u32 v18, v2, 16, 1
	v_add3_u32 v2, v2, v18, s68
	ds_write_b16_d16_hi v70, v2 offset:53440
	v_mul_f32_e32 v2, v3, v83
	v_bfe_u32 v3, v2, 16, 1
	v_add3_u32 v2, v2, v3, s68
	ds_write_b16_d16_hi v70, v2 offset:53520
	v_mul_f32_e32 v2, v51, v83
	v_bfe_u32 v3, v2, 16, 1
	v_add3_u32 v2, v2, v3, s68
	ds_write_b16_d16_hi v70, v2 offset:53584
	v_mul_f32_e32 v2, v35, v83
	v_bfe_u32 v3, v2, 16, 1
	v_add3_u32 v2, v2, v3, s68
	ds_write_b16_d16_hi v70, v2 offset:53648
	v_mul_f32_e32 v2, v19, v83
	v_bfe_u32 v3, v2, 16, 1
	v_add3_u32 v2, v2, v3, s68
	ds_write_b16_d16_hi v70, v2 offset:53712
	v_mul_f32_e32 v2, v4, v84
	v_bfe_u32 v3, v2, 16, 1
	v_add3_u32 v2, v2, v3, s68
	ds_write_b16_d16_hi v70, v2 offset:53792
	v_mul_f32_e32 v2, v52, v84
	v_bfe_u32 v3, v2, 16, 1
	v_add3_u32 v2, v2, v3, s68
	ds_write_b16_d16_hi v70, v2 offset:53856
	v_mul_f32_e32 v2, v36, v84
	v_bfe_u32 v3, v2, 16, 1
	v_add3_u32 v2, v2, v3, s68
	ds_write_b16_d16_hi v70, v2 offset:53920
	v_mul_f32_e32 v2, v20, v84
	v_bfe_u32 v3, v2, 16, 1
	v_add3_u32 v2, v2, v3, s68
	ds_write_b16_d16_hi v70, v2 offset:53984
	v_mul_f32_e32 v2, v5, v85
	v_bfe_u32 v3, v2, 16, 1
	v_add3_u32 v2, v2, v3, s68
	ds_write_b16_d16_hi v70, v2 offset:54064
	v_mul_f32_e32 v2, v53, v85
	v_bfe_u32 v3, v2, 16, 1
	v_add3_u32 v2, v2, v3, s68
	ds_write_b16_d16_hi v70, v2 offset:54128
	v_mul_f32_e32 v2, v37, v85
	v_bfe_u32 v3, v2, 16, 1
	v_add3_u32 v2, v2, v3, s68
	ds_write_b16_d16_hi v70, v2 offset:54192
	v_mul_f32_e32 v2, v21, v85
	v_bfe_u32 v3, v2, 16, 1
	v_add3_u32 v2, v2, v3, s68
	ds_write_b16_d16_hi v70, v2 offset:54256
	v_mul_f32_e32 v2, v6, v86
	v_bfe_u32 v3, v2, 16, 1
	v_add3_u32 v2, v2, v3, s68
	ds_write_b16_d16_hi v70, v2 offset:55424
	v_mul_f32_e32 v2, v54, v86
	v_bfe_u32 v3, v2, 16, 1
	v_add3_u32 v2, v2, v3, s68
	ds_write_b16_d16_hi v70, v2 offset:55488
	v_mul_f32_e32 v2, v38, v86
	v_bfe_u32 v3, v2, 16, 1
	v_add3_u32 v2, v2, v3, s68
	ds_write_b16_d16_hi v70, v2 offset:55552
	v_mul_f32_e32 v2, v22, v86
	v_bfe_u32 v3, v2, 16, 1
	v_add3_u32 v2, v2, v3, s68
	ds_write_b16_d16_hi v70, v2 offset:55616
	v_mul_f32_e32 v2, v7, v87
	v_bfe_u32 v3, v2, 16, 1
	v_add3_u32 v2, v2, v3, s68
	ds_write_b16_d16_hi v70, v2 offset:55696
	v_mul_f32_e32 v2, v55, v87
	v_bfe_u32 v3, v2, 16, 1
	v_add3_u32 v2, v2, v3, s68
	ds_write_b16_d16_hi v70, v2 offset:55760
	v_mul_f32_e32 v2, v39, v87
	v_bfe_u32 v3, v2, 16, 1
	v_add3_u32 v2, v2, v3, s68
	ds_write_b16_d16_hi v70, v2 offset:55824
	v_mul_f32_e32 v2, v23, v87
	v_bfe_u32 v3, v2, 16, 1
	v_add3_u32 v2, v2, v3, s68
	ds_write_b16_d16_hi v70, v2 offset:55888
	v_mul_f32_e32 v2, v8, v88
	v_bfe_u32 v3, v2, 16, 1
	v_add3_u32 v2, v2, v3, s68
	ds_write_b16_d16_hi v70, v2 offset:55968
	v_mul_f32_e32 v2, v56, v88
	v_bfe_u32 v3, v2, 16, 1
	v_add3_u32 v2, v2, v3, s68
	ds_write_b16_d16_hi v70, v2 offset:56032
	v_mul_f32_e32 v2, v40, v88
	v_bfe_u32 v3, v2, 16, 1
	v_add3_u32 v2, v2, v3, s68
	ds_write_b16_d16_hi v70, v2 offset:56096
	v_mul_f32_e32 v2, v24, v88
	v_bfe_u32 v3, v2, 16, 1
	v_add3_u32 v2, v2, v3, s68
	ds_write_b16_d16_hi v70, v2 offset:56160
	v_mul_f32_e32 v2, v9, v89
	v_bfe_u32 v3, v2, 16, 1
	v_add3_u32 v2, v2, v3, s68
	ds_write_b16_d16_hi v70, v2 offset:56240
	v_mul_f32_e32 v2, v57, v89
	v_bfe_u32 v3, v2, 16, 1
	v_add3_u32 v2, v2, v3, s68
	ds_write_b16_d16_hi v70, v2 offset:56304
	v_mul_f32_e32 v2, v41, v89
	v_bfe_u32 v3, v2, 16, 1
	v_add3_u32 v2, v2, v3, s68
	ds_write_b16_d16_hi v70, v2 offset:56368
	v_mul_f32_e32 v2, v25, v89
	v_bfe_u32 v3, v2, 16, 1
	v_add3_u32 v2, v2, v3, s68
	ds_write_b16_d16_hi v70, v2 offset:56432
	v_mul_f32_e32 v2, v10, v74
	v_bfe_u32 v3, v2, 16, 1
	v_add3_u32 v2, v2, v3, s68
	ds_write_b16_d16_hi v70, v2 offset:57600
	v_mul_f32_e32 v2, v58, v74
	v_bfe_u32 v3, v2, 16, 1
	v_add3_u32 v2, v2, v3, s68
	ds_write_b16_d16_hi v70, v2 offset:57664
	v_mul_f32_e32 v2, v42, v74
	v_bfe_u32 v3, v2, 16, 1
	v_add3_u32 v2, v2, v3, s68
	ds_write_b16_d16_hi v70, v2 offset:57728
	v_mul_f32_e32 v2, v26, v74
	v_bfe_u32 v3, v2, 16, 1
	v_add3_u32 v2, v2, v3, s68
	ds_write_b16_d16_hi v70, v2 offset:57792
	v_mul_f32_e32 v2, v11, v75
	v_bfe_u32 v3, v2, 16, 1
	v_add3_u32 v2, v2, v3, s68
	ds_write_b16_d16_hi v70, v2 offset:57872
	v_mul_f32_e32 v2, v59, v75
	v_bfe_u32 v3, v2, 16, 1
	v_add3_u32 v2, v2, v3, s68
	ds_write_b16_d16_hi v70, v2 offset:57936
	v_mul_f32_e32 v2, v43, v75
	v_bfe_u32 v3, v2, 16, 1
	v_add3_u32 v2, v2, v3, s68
	ds_write_b16_d16_hi v70, v2 offset:58000
	v_mul_f32_e32 v2, v27, v75
	v_bfe_u32 v3, v2, 16, 1
	v_add3_u32 v2, v2, v3, s68
	ds_write_b16_d16_hi v70, v2 offset:58064
	v_mul_f32_e32 v2, v12, v76
	v_bfe_u32 v3, v2, 16, 1
	v_add3_u32 v2, v2, v3, s68
	ds_write_b16_d16_hi v70, v2 offset:58144
	v_mul_f32_e32 v2, v60, v76
	v_bfe_u32 v3, v2, 16, 1
	v_add3_u32 v2, v2, v3, s68
	ds_write_b16_d16_hi v70, v2 offset:58208
	v_mul_f32_e32 v2, v44, v76
	v_bfe_u32 v3, v2, 16, 1
	v_add3_u32 v2, v2, v3, s68
	ds_write_b16_d16_hi v70, v2 offset:58272
	v_mul_f32_e32 v2, v28, v76
	v_bfe_u32 v3, v2, 16, 1
	v_add3_u32 v2, v2, v3, s68
	ds_write_b16_d16_hi v70, v2 offset:58336
	v_mul_f32_e32 v2, v13, v77
	v_bfe_u32 v3, v2, 16, 1
	v_add3_u32 v2, v2, v3, s68
	ds_write_b16_d16_hi v70, v2 offset:58416
	v_mul_f32_e32 v2, v61, v77
	v_bfe_u32 v3, v2, 16, 1
	v_add3_u32 v2, v2, v3, s68
	ds_write_b16_d16_hi v70, v2 offset:58480
	v_mul_f32_e32 v2, v45, v77
	v_bfe_u32 v3, v2, 16, 1
	v_add3_u32 v2, v2, v3, s68
	ds_write_b16_d16_hi v70, v2 offset:58544
	v_mul_f32_e32 v2, v29, v77
	v_bfe_u32 v3, v2, 16, 1
	v_add3_u32 v2, v2, v3, s68
	ds_write_b16_d16_hi v70, v2 offset:58608
	v_mul_f32_e32 v2, v14, v78
	v_bfe_u32 v3, v2, 16, 1
	v_add3_u32 v2, v2, v3, s68
	ds_write_b16_d16_hi v70, v2 offset:59776
	v_mul_f32_e32 v2, v62, v78
	v_bfe_u32 v3, v2, 16, 1
	v_add3_u32 v2, v2, v3, s68
	ds_write_b16_d16_hi v70, v2 offset:59840
	v_mul_f32_e32 v2, v46, v78
	v_bfe_u32 v3, v2, 16, 1
	v_rcp_f32_e32 v66, v79
	v_add3_u32 v2, v2, v3, s68
	ds_write_b16_d16_hi v70, v2 offset:59904
	v_mul_f32_e32 v2, v30, v78
	v_bfe_u32 v3, v2, 16, 1
	v_add3_u32 v2, v2, v3, s68
	ds_write_b16_d16_hi v70, v2 offset:59968
	v_mul_f32_e32 v2, v15, v66
	v_bfe_u32 v3, v2, 16, 1
	v_add3_u32 v2, v2, v3, s68
	ds_write_b16_d16_hi v70, v2 offset:60048
	v_mul_f32_e32 v2, v63, v66
	v_bfe_u32 v3, v2, 16, 1
	v_add3_u32 v2, v2, v3, s68
	ds_write_b16_d16_hi v70, v2 offset:60112
	v_mul_f32_e32 v2, v47, v66
	v_bfe_u32 v3, v2, 16, 1
	v_rcp_f32_e32 v67, v80
	v_add3_u32 v2, v2, v3, s68
	ds_write_b16_d16_hi v70, v2 offset:60176
	v_mul_f32_e32 v2, v31, v66
	v_bfe_u32 v3, v2, 16, 1
	v_add3_u32 v2, v2, v3, s68
	ds_write_b16_d16_hi v70, v2 offset:60240
	v_mul_f32_e32 v2, v16, v67
	v_bfe_u32 v3, v2, 16, 1
	v_add3_u32 v2, v2, v3, s68
	ds_write_b16_d16_hi v70, v2 offset:60320
	v_mul_f32_e32 v2, v64, v67
	v_bfe_u32 v3, v2, 16, 1
	v_add3_u32 v2, v2, v3, s68
	ds_write_b16_d16_hi v70, v2 offset:60384
	v_mul_f32_e32 v2, v48, v67
	v_bfe_u32 v3, v2, 16, 1
	v_rcp_f32_e32 v68, v81
	v_add3_u32 v2, v2, v3, s68
	ds_write_b16_d16_hi v70, v2 offset:60448
	v_mul_f32_e32 v2, v32, v67
	v_bfe_u32 v3, v2, 16, 1
	v_add3_u32 v2, v2, v3, s68
	ds_write_b16_d16_hi v70, v2 offset:60512
	v_mul_f32_e32 v2, v17, v68
	v_bfe_u32 v3, v2, 16, 1
	v_add3_u32 v2, v2, v3, s68
	ds_write_b16_d16_hi v70, v2 offset:60592
	v_mul_f32_e32 v2, v65, v68
	v_bfe_u32 v3, v2, 16, 1
	v_add3_u32 v2, v2, v3, s68
	ds_write_b16_d16_hi v70, v2 offset:60656
	v_mul_f32_e32 v2, v49, v68
	v_bfe_u32 v3, v2, 16, 1
	v_add3_u32 v2, v2, v3, s68
	ds_write_b16_d16_hi v70, v2 offset:60720
	v_mul_f32_e32 v2, v33, v68
	v_bfe_u32 v3, v2, 16, 1
	v_add3_u32 v2, v2, v3, s68
	ds_write_b16_d16_hi v70, v2 offset:60784
	v_lshrrev_b32_e32 v2, 1, v154
	v_lshlrev_b32_e32 v3, 1, v178
	v_and_b32_e32 v36, 2, v3
	v_mad_u32_u24 v37, v2, s69, v69
	s_waitcnt lgkmcnt(0)
	v_lshl_add_u32 v14, v36, 6, v37
	v_or_b32_e32 v8, v179, v2
	ds_read_b128 v[2:5], v14 offset:53248
	v_mov_b64_e32 v[6:7], s[6:7]
	v_mad_i64_i32 v[34:35], s[6:7], v8, s66, v[6:7]
	ds_read_b128 v[6:9], v14 offset:53280
	ds_read_b128 v[10:13], v14 offset:53264
	ds_read_b128 v[14:17], v14 offset:53296
	s_waitcnt lgkmcnt(3)
	v_and_b32_e32 v19, 0xffff0000, v2
	v_lshlrev_b32_e32 v2, 16, v2
	s_waitcnt lgkmcnt(2)
	v_and_b32_e32 v20, 0xffff0000, v6
	v_lshlrev_b32_e32 v6, 16, v6
	v_and_b32_e32 v21, 0xffff0000, v3
	v_lshlrev_b32_e32 v22, 16, v3
	v_and_b32_e32 v24, 0xffff0000, v4
	v_lshlrev_b32_e32 v25, 16, v4
	v_max_f32_e64 v3, |v6|, |v6|
	v_max_f32_e64 v4, |v2|, |v2|
	v_and_b32_e32 v27, 0xffff0000, v5
	v_lshlrev_b32_e32 v28, 16, v5
	v_max_f32_e32 v3, v4, v3
	v_max_f32_e64 v4, |v20|, |v20|
	v_max_f32_e64 v5, |v19|, |v19|
	v_and_b32_e32 v23, 0xffff0000, v7
	v_lshlrev_b32_e32 v7, 16, v7
	v_max_f32_e32 v4, v5, v4
	v_max3_f32 v3, v3, 0, v4
	v_max_f32_e64 v4, |v7|, |v7|
	v_max_f32_e64 v5, |v22|, |v22|
	s_waitcnt lgkmcnt(1)
	v_and_b32_e32 v32, 0xffff0000, v11
	v_lshlrev_b32_e32 v33, 16, v11
	v_max_f32_e32 v4, v5, v4
	v_max_f32_e64 v5, |v23|, |v23|
	v_max_f32_e64 v11, |v21|, |v21|
	v_and_b32_e32 v26, 0xffff0000, v8
	v_lshlrev_b32_e32 v8, 16, v8
	v_max_f32_e32 v5, v11, v5
	v_max3_f32 v3, v3, v4, v5
	v_max_f32_e64 v4, |v8|, |v8|
	v_max_f32_e64 v5, |v25|, |v25|
	v_max_f32_e32 v4, v5, v4
	v_max_f32_e64 v5, |v26|, |v26|
	v_max_f32_e64 v11, |v24|, |v24|
	v_and_b32_e32 v29, 0xffff0000, v9
	v_lshlrev_b32_e32 v9, 16, v9
	v_max_f32_e32 v5, v11, v5
	v_max3_f32 v3, v3, v4, v5
	v_max_f32_e64 v4, |v9|, |v9|
	v_max_f32_e64 v5, |v28|, |v28|
	v_max_f32_e32 v4, v5, v4
	v_max_f32_e64 v5, |v29|, |v29|
	v_max_f32_e64 v11, |v27|, |v27|
	v_and_b32_e32 v30, 0xffff0000, v10
	v_lshlrev_b32_e32 v10, 16, v10
	s_waitcnt lgkmcnt(0)
	v_and_b32_e32 v31, 0xffff0000, v14
	v_lshlrev_b32_e32 v14, 16, v14
	v_max_f32_e32 v5, v11, v5
	v_max3_f32 v3, v3, v4, v5
	v_max_f32_e64 v4, |v14|, |v14|
	v_max_f32_e64 v5, |v10|, |v10|
	v_max_f32_e32 v4, v5, v4
	v_max_f32_e64 v5, |v31|, |v31|
	v_max_f32_e64 v11, |v30|, |v30|
	v_and_b32_e32 v38, 0xffff0000, v15
	v_lshlrev_b32_e32 v15, 16, v15
	v_max_f32_e32 v5, v11, v5
	v_max3_f32 v3, v3, v4, v5
	v_max_f32_e64 v4, |v15|, |v15|
	v_max_f32_e64 v5, |v33|, |v33|
	v_max_f32_e32 v4, v5, v4
	v_max_f32_e64 v5, |v38|, |v38|
	v_max_f32_e64 v11, |v32|, |v32|
	v_lshlrev_b32_e32 v40, 16, v12
	v_and_b32_e32 v41, 0xffff0000, v16
	v_lshlrev_b32_e32 v16, 16, v16
	v_max_f32_e32 v5, v11, v5
	v_and_b32_e32 v39, 0xffff0000, v12
	v_max3_f32 v3, v3, v4, v5
	v_max_f32_e64 v4, |v16|, |v16|
	v_max_f32_e64 v5, |v40|, |v40|
	v_max_f32_e32 v4, v5, v4
	v_max_f32_e64 v5, |v41|, |v41|
	v_max_f32_e64 v11, |v39|, |v39|
	v_lshlrev_b32_e32 v43, 16, v13
	v_and_b32_e32 v44, 0xffff0000, v17
	v_lshlrev_b32_e32 v17, 16, v17
	v_max_f32_e32 v5, v11, v5
	v_and_b32_e32 v42, 0xffff0000, v13
	v_max3_f32 v3, v3, v4, v5
	v_max_f32_e64 v4, |v17|, |v17|
	v_max_f32_e64 v5, |v43|, |v43|
	v_max_f32_e32 v4, v5, v4
	v_max_f32_e64 v5, |v44|, |v44|
	v_max_f32_e64 v11, |v42|, |v42|
	v_max_f32_e32 v5, v11, v5
	v_max3_f32 v3, v3, v4, v5
	v_bfe_u32 v3, v3, 23, 8
	v_max_u32_e32 v45, 3, v3
	v_lshlrev_b32_e32 v3, 23, v45
	v_sub_u32_e32 v46, 0x80000000, v3
	v_mul_f32_e32 v3, v6, v46
	v_mul_f32_e32 v5, v7, v46
	v_mul_f32_e32 v6, v23, v46
	v_mul_f32_e32 v11, v29, v46
	v_mul_f32_e32 v4, v20, v46
	v_med3_f32 v20, v5, s70, v177
	v_mul_f32_e32 v5, v21, v46
	v_med3_f32 v21, v6, s70, v177
	v_mul_f32_e32 v6, v25, v46
	v_mul_f32_e32 v7, v8, v46
	v_mul_f32_e32 v8, v26, v46
	v_mul_f32_e32 v9, v9, v46
	v_med3_f32 v25, v11, s70, v177
	v_mul_f32_e32 v11, v14, v46
	v_mul_f32_e32 v12, v31, v46
	v_mul_f32_e32 v13, v15, v46
	v_mul_f32_e32 v14, v38, v46
	v_mul_f32_e32 v15, v16, v46
	v_mul_f32_e32 v16, v41, v46
	v_mul_f32_e32 v17, v17, v46
	v_mul_f32_e32 v2, v2, v46
	v_med3_f32 v18, v3, s70, v177
	v_mul_f32_e32 v3, v19, v46
	v_med3_f32 v19, v4, s70, v177
	v_mul_f32_e32 v4, v22, v46
	v_med3_f32 v22, v7, s70, v177
	v_mul_f32_e32 v7, v24, v46
	v_med3_f32 v23, v8, s70, v177
	v_mul_f32_e32 v8, v28, v46
	v_med3_f32 v24, v9, s70, v177
	v_mul_f32_e32 v9, v27, v46
	v_mul_f32_e32 v10, v10, v46
	v_med3_f32 v26, v11, s70, v177
	v_mul_f32_e32 v11, v30, v46
	v_med3_f32 v27, v12, s70, v177
	v_mul_f32_e32 v12, v33, v46
	v_med3_f32 v28, v13, s70, v177
	v_mul_f32_e32 v13, v32, v46
	v_med3_f32 v29, v14, s70, v177
	v_mul_f32_e32 v14, v40, v46
	v_med3_f32 v30, v15, s70, v177
	v_mul_f32_e32 v15, v39, v46
	v_med3_f32 v31, v16, s70, v177
	v_mul_f32_e32 v16, v43, v46
	v_med3_f32 v32, v17, s70, v177
	v_mul_f32_e32 v17, v42, v46
	v_mul_f32_e32 v33, v44, v46
	v_med3_f32 v2, v2, s70, v177
	v_med3_f32 v3, v3, s70, v177
	v_med3_f32 v4, v4, s70, v177
	v_med3_f32 v5, v5, s70, v177
	v_med3_f32 v6, v6, s70, v177
	v_med3_f32 v7, v7, s70, v177
	v_med3_f32 v8, v8, s70, v177
	v_med3_f32 v9, v9, s70, v177
	v_med3_f32 v10, v10, s70, v177
	v_med3_f32 v11, v11, s70, v177
	v_med3_f32 v12, v12, s70, v177
	v_med3_f32 v13, v13, s70, v177
	v_med3_f32 v14, v14, s70, v177
	v_med3_f32 v15, v15, s70, v177
	v_med3_f32 v16, v16, s70, v177
	v_med3_f32 v17, v17, s70, v177
	v_med3_f32 v33, v33, s70, v177
	v_cvt_scalef32_2xpk16_fp6_f32 v[2:7], v[2:17], v[18:33], 1.0
	v_mov_b32_e32 v152, v6
	v_mov_b32_e32 v153, v7
	v_lshlrev_b32_e32 v6, 4, v36
	v_mov_b32_e32 v7, v155
	v_lshl_add_u64 v[10:11], v[34:35], 0, v[6:7]
	v_or_b32_e32 v36, 1, v36
	global_store_dwordx4 v[10:11], v[2:5], off
	v_lshl_add_u32 v14, v36, 6, v37
	ds_read_b128 v[2:5], v14 offset:53248
	ds_read_b128 v[6:9], v14 offset:53280
	v_add_u32_e32 v154, -2, v45
	global_store_dwordx4 v[10:11], v[152:155], off offset:64
	ds_read_b128 v[10:13], v14 offset:53264
	ds_read_b128 v[14:17], v14 offset:53296
	s_waitcnt lgkmcnt(3)
	v_lshlrev_b32_e32 v18, 16, v2
	s_waitcnt lgkmcnt(2)
	v_lshlrev_b32_e32 v19, 16, v6
	v_and_b32_e32 v20, 0xffff0000, v2
	v_and_b32_e32 v6, 0xffff0000, v6
	v_lshlrev_b32_e32 v21, 16, v3
	v_and_b32_e32 v23, 0xffff0000, v3
	v_max_f32_e64 v2, |v19|, |v19|
	v_max_f32_e64 v3, |v18|, |v18|
	v_lshlrev_b32_e32 v24, 16, v4
	v_and_b32_e32 v26, 0xffff0000, v4
	v_max_f32_e32 v2, v3, v2
	v_max_f32_e64 v3, |v6|, |v6|
	v_max_f32_e64 v4, |v20|, |v20|
	v_lshlrev_b32_e32 v22, 16, v7
	v_max_f32_e32 v3, v4, v3
	v_and_b32_e32 v7, 0xffff0000, v7
	v_max3_f32 v2, v2, 0, v3
	v_max_f32_e64 v3, |v22|, |v22|
	v_max_f32_e64 v4, |v21|, |v21|
	v_lshlrev_b32_e32 v27, 16, v5
	v_and_b32_e32 v29, 0xffff0000, v5
	v_max_f32_e32 v3, v4, v3
	v_max_f32_e64 v4, |v7|, |v7|
	v_max_f32_e64 v5, |v23|, |v23|
	v_lshlrev_b32_e32 v25, 16, v8
	v_max_f32_e32 v4, v5, v4
	v_and_b32_e32 v8, 0xffff0000, v8
	v_max3_f32 v2, v2, v3, v4
	v_max_f32_e64 v3, |v25|, |v25|
	v_max_f32_e64 v4, |v24|, |v24|
	v_max_f32_e32 v3, v4, v3
	v_max_f32_e64 v4, |v8|, |v8|
	v_max_f32_e64 v5, |v26|, |v26|
	v_lshlrev_b32_e32 v28, 16, v9
	v_max_f32_e32 v4, v5, v4
	v_and_b32_e32 v30, 0xffff0000, v9
	v_max3_f32 v2, v2, v3, v4
	v_max_f32_e64 v3, |v28|, |v28|
	v_max_f32_e64 v4, |v27|, |v27|
	v_max_f32_e32 v3, v4, v3
	v_max_f32_e64 v4, |v30|, |v30|
	v_max_f32_e64 v5, |v29|, |v29|
	s_waitcnt lgkmcnt(1)
	v_lshlrev_b32_e32 v31, 16, v10
	s_waitcnt lgkmcnt(0)
	v_lshlrev_b32_e32 v32, 16, v14
	v_max_f32_e32 v4, v5, v4
	v_and_b32_e32 v33, 0xffff0000, v10
	v_and_b32_e32 v14, 0xffff0000, v14
	v_max3_f32 v2, v2, v3, v4
	v_max_f32_e64 v3, |v32|, |v32|
	v_max_f32_e64 v4, |v31|, |v31|
	v_max_f32_e32 v3, v4, v3
	v_max_f32_e64 v4, |v14|, |v14|
	v_max_f32_e64 v5, |v33|, |v33|
	v_lshlrev_b32_e32 v37, 16, v11
	v_lshlrev_b32_e32 v38, 16, v15
	v_max_f32_e32 v4, v5, v4
	v_and_b32_e32 v39, 0xffff0000, v11
	v_and_b32_e32 v15, 0xffff0000, v15
	v_max3_f32 v2, v2, v3, v4
	v_max_f32_e64 v3, |v38|, |v38|
	v_max_f32_e64 v4, |v37|, |v37|
	v_max_f32_e32 v3, v4, v3
	v_max_f32_e64 v4, |v15|, |v15|
	v_max_f32_e64 v5, |v39|, |v39|
	v_lshlrev_b32_e32 v40, 16, v12
	v_lshlrev_b32_e32 v41, 16, v16
	v_max_f32_e32 v4, v5, v4
	v_and_b32_e32 v42, 0xffff0000, v12
	v_and_b32_e32 v16, 0xffff0000, v16
	v_max3_f32 v2, v2, v3, v4
	v_max_f32_e64 v3, |v41|, |v41|
	v_max_f32_e64 v4, |v40|, |v40|
	v_max_f32_e32 v3, v4, v3
	v_max_f32_e64 v4, |v16|, |v16|
	v_max_f32_e64 v5, |v42|, |v42|
	v_lshlrev_b32_e32 v43, 16, v13
	v_lshlrev_b32_e32 v44, 16, v17
	v_max_f32_e32 v4, v5, v4
	v_and_b32_e32 v45, 0xffff0000, v13
	v_and_b32_e32 v46, 0xffff0000, v17
	v_max3_f32 v2, v2, v3, v4
	v_max_f32_e64 v3, |v44|, |v44|
	v_max_f32_e64 v4, |v43|, |v43|
	v_max_f32_e32 v3, v4, v3
	v_max_f32_e64 v4, |v46|, |v46|
	v_max_f32_e64 v5, |v45|, |v45|
	v_max_f32_e32 v4, v5, v4
	v_max3_f32 v2, v2, v3, v4
	v_bfe_u32 v2, v2, 23, 8
	v_max_u32_e32 v47, 3, v2
	v_lshlrev_b32_e32 v2, 23, v47
	v_sub_u32_e32 v48, 0x80000000, v2
	v_mul_f32_e32 v3, v19, v48
	v_mul_f32_e32 v4, v6, v48
	v_mul_f32_e32 v5, v22, v48
	v_mul_f32_e32 v6, v7, v48
	v_mul_f32_e32 v7, v25, v48
	v_mul_f32_e32 v8, v8, v48
	v_mul_f32_e32 v9, v28, v48
	v_mul_f32_e32 v10, v30, v48
	v_mul_f32_e32 v11, v32, v48
	v_mul_f32_e32 v12, v14, v48
	v_mul_f32_e32 v13, v38, v48
	v_mul_f32_e32 v14, v15, v48
	v_mul_f32_e32 v15, v41, v48
	v_mul_f32_e32 v16, v16, v48
	v_mul_f32_e32 v17, v44, v48
	v_mul_f32_e32 v2, v18, v48
	v_med3_f32 v18, v3, s70, v177
	v_mul_f32_e32 v3, v20, v48
	v_med3_f32 v19, v4, s70, v177
	v_mul_f32_e32 v4, v21, v48
	v_med3_f32 v20, v5, s70, v177
	v_mul_f32_e32 v5, v23, v48
	v_med3_f32 v21, v6, s70, v177
	v_mul_f32_e32 v6, v24, v48
	v_med3_f32 v22, v7, s70, v177
	v_mul_f32_e32 v7, v26, v48
	v_med3_f32 v23, v8, s70, v177
	v_mul_f32_e32 v8, v27, v48
	v_med3_f32 v24, v9, s70, v177
	v_mul_f32_e32 v9, v29, v48
	v_med3_f32 v25, v10, s70, v177
	v_mul_f32_e32 v10, v31, v48
	v_med3_f32 v26, v11, s70, v177
	v_mul_f32_e32 v11, v33, v48
	v_med3_f32 v27, v12, s70, v177
	v_mul_f32_e32 v12, v37, v48
	v_med3_f32 v28, v13, s70, v177
	v_mul_f32_e32 v13, v39, v48
	v_med3_f32 v29, v14, s70, v177
	v_mul_f32_e32 v14, v40, v48
	v_med3_f32 v30, v15, s70, v177
	v_mul_f32_e32 v15, v42, v48
	v_med3_f32 v31, v16, s70, v177
	v_mul_f32_e32 v16, v43, v48
	v_med3_f32 v32, v17, s70, v177
	v_mul_f32_e32 v17, v45, v48
	v_mul_f32_e32 v33, v46, v48
	v_med3_f32 v2, v2, s70, v177
	v_med3_f32 v3, v3, s70, v177
	v_med3_f32 v4, v4, s70, v177
	v_med3_f32 v5, v5, s70, v177
	v_med3_f32 v6, v6, s70, v177
	v_med3_f32 v7, v7, s70, v177
	v_med3_f32 v8, v8, s70, v177
	v_med3_f32 v9, v9, s70, v177
	v_med3_f32 v10, v10, s70, v177
	v_med3_f32 v11, v11, s70, v177
	v_med3_f32 v12, v12, s70, v177
	v_med3_f32 v13, v13, s70, v177
	v_med3_f32 v14, v14, s70, v177
	v_med3_f32 v15, v15, s70, v177
	v_med3_f32 v16, v16, s70, v177
	v_med3_f32 v17, v17, s70, v177
	v_med3_f32 v33, v33, s70, v177
	v_cvt_scalef32_2xpk16_fp6_f32 v[2:7], v[2:17], v[18:33], 1.0
	v_mov_b32_e32 v152, v6
	v_mov_b32_e32 v153, v7
	v_lshlrev_b32_e32 v6, 4, v36
	v_mov_b32_e32 v7, v155
	v_lshl_add_u64 v[6:7], v[34:35], 0, v[6:7]
	v_add_u32_e32 v154, -2, v47
	global_store_dwordx4 v[6:7], v[2:5], off
	global_store_dwordx4 v[6:7], v[152:155], off offset:64
	s_barrier
	s_cbranch_scc1 .LBB0_712

.LBB0_694:
	ds_read_b128 v[80:83], v196 offset:28672
	ds_read_b128 v[76:79], v194 offset:28672
	ds_read_b128 v[146:149], v194 offset:34816
	ds_read_b128 v[150:153], v196 offset:34816
	ds_read_b128 v[164:167], v198 offset:28672
	ds_read_b128 v[204:207], v198 offset:34816
	ds_read_b128 v[168:171], v199 offset:28672
	ds_read_b128 v[208:211], v199 offset:34816
	ds_read_b128 v[212:215], v201 offset:28672
	ds_read_b128 v[220:223], v201 offset:34816
	s_waitcnt lgkmcnt(8)
	v_mfma_scale_f32_32x32x64_f8f6f4 v[82:97], v[76:83], v[114:121], 0, v1, v1 op_sel_hi:[0,0,0]
	v_exp_f32_e32 v129, v70
	v_exp_f32_e32 v174, v71
	v_exp_f32_e32 v175, v68
	v_exp_f32_e32 v228, v69
	v_exp_f32_e32 v229, v66
	v_exp_f32_e32 v230, v67
	v_exp_f32_e32 v231, v74
	v_exp_f32_e32 v232, v75
	v_exp_f32_e32 v233, v72
	v_exp_f32_e32 v234, v73
	v_exp_f32_e32 v124, v124
	v_exp_f32_e32 v125, v125
	v_exp_f32_e32 v122, v122
	ds_read_b128 v[216:219], v200 offset:28672
	ds_read_b128 v[224:227], v200 offset:34816
	ds_read_b128 v[244:247], v189
	ds_read_b128 v[248:251], v190
	v_exp_f32_e32 v123, v123
	s_waitcnt lgkmcnt(10)
	v_mfma_scale_f32_32x32x64_f8f6f4 v[66:81], v[146:153], v[114:121], 0, v1, v1 op_sel_hi:[0,0,0]
	v_add_f32_e32 v146, 0, v144
	v_add_f32_e32 v146, v145, v146
	v_add_f32_e32 v146, v136, v146
	v_add_f32_e32 v146, v138, v146
	v_add_f32_e32 v146, v142, v146
	v_add_f32_e32 v146, v143, v146
	v_add_f32_e32 v146, v140, v146
	v_add_f32_e32 v146, v141, v146
	v_add_f32_e32 v146, v137, v146
	v_add_f32_e32 v146, v139, v146
	v_add_f32_e32 v146, v130, v146
	v_add_f32_e32 v146, v131, v146
	v_add_f32_e32 v146, v134, v146
	v_add_f32_e32 v146, v135, v146
	v_add_f32_e32 v146, v132, v146
	s_waitcnt lgkmcnt(7)
	v_mfma_scale_f32_32x32x64_f8f6f4 v[82:97], v[164:171], v[106:113], v[82:97], v1, v1 op_sel_hi:[0,0,0]
	v_add_f32_e32 v146, v133, v146
	v_add_f32_e32 v146, v124, v146
	v_add_f32_e32 v146, v125, v146
	v_add_f32_e32 v146, v122, v146
	v_add_f32_e32 v146, v123, v146
	v_add_f32_e32 v146, v129, v146
	v_add_f32_e32 v146, v174, v146
	v_add_f32_e32 v146, v175, v146
	v_add_f32_e32 v146, v228, v146
	v_add_f32_e32 v146, v229, v146
	v_add_f32_e32 v146, v230, v146
	v_exp_f32_e32 v126, v126
	v_add_f32_e32 v146, v231, v146
	v_exp_f32_e32 v127, v127
	v_add_f32_e32 v146, v232, v146
	s_waitcnt lgkmcnt(6)
	v_mfma_scale_f32_32x32x64_f8f6f4 v[66:81], v[204:211], v[106:113], v[66:81], v1, v1 op_sel_hi:[0,0,0]
	v_add_f32_e32 v146, v233, v146
	v_add_f32_e32 v146, v234, v146
	v_add_f32_e32 v146, v126, v146
	v_add_f32_e32 v203, v127, v146
	v_cvt_pk_fp8_f32 v146, v144, v145
	v_cvt_pk_fp8_f32 v150, v124, v125
	v_cvt_pk_fp8_f32 v147, v142, v143
	s_waitcnt lgkmcnt(3)
	v_mfma_scale_f32_32x32x64_f8f6f4 v[82:97], v[212:219], v[98:105], v[82:97], v1, v1 op_sel_hi:[0,0,0]
	v_cvt_pk_fp8_f32 v151, v129, v174
	v_cvt_pk_fp8_f32 v148, v137, v139
	v_cvt_pk_fp8_f32 v152, v229, v230
	v_cvt_pk_fp8_f32 v149, v134, v135
	v_cvt_pk_fp8_f32 v153, v233, v234
	v_mov_b32_e32 v204, v203
	s_nop 1
	v_permlane32_swap_b32_e32 v203, v204
	v_cvt_pk_fp8_f32 v146, v136, v138 op_sel:[0,0,1]
	v_cvt_pk_fp8_f32 v150, v122, v123 op_sel:[0,0,1]
	v_cvt_pk_fp8_f32 v147, v140, v141 op_sel:[0,0,1]
	v_cvt_pk_fp8_f32 v151, v175, v228 op_sel:[0,0,1]
	v_cvt_pk_fp8_f32 v148, v130, v131 op_sel:[0,0,1]
	v_cvt_pk_fp8_f32 v152, v231, v232 op_sel:[0,0,1]
	v_cvt_pk_fp8_f32 v149, v132, v133 op_sel:[0,0,1]
	s_waitcnt lgkmcnt(2)
	v_mfma_scale_f32_32x32x64_f8f6f4 v[66:81], v[220:227], v[98:105], v[66:81], v1, v1 op_sel_hi:[0,0,0]
	v_cvt_pk_fp8_f32 v153, v126, v127 op_sel:[0,0,1]
	s_add_i32 s8, s11, 0xffffe000
	s_add_i32 s9, s72, 0xffffd000
	buffer_load_dwordx4 v[164:167], v191, s[40:43], s8 offen
	buffer_load_dwordx4 v[168:171], v191, s[36:39], s9 offen
	buffer_load_dwordx2 v[174:175], v192, s[36:39], s9 offen
	v_max_f32_e32 v122, v83, v83
	v_max_f32_e32 v123, v82, v82
	v_max_f32_e32 v122, v123, v122
	v_max3_f32 v122, v122, v84, v85
	v_max3_f32 v122, v122, v86, v87
	v_max3_f32 v122, v122, v88, v89
	v_max3_f32 v122, v122, v90, v91
	ds_read_b128 v[138:141], v187 offset:2048
	ds_read_b128 v[206:209], v187 offset:4096
	v_max3_f32 v122, v122, v92, v93
	v_max3_f32 v122, v122, v94, v95
	v_max3_f32 v122, v122, v96, v97
	s_waitcnt lgkmcnt(2)
	v_mfma_scale_f32_32x32x64_f8f6f4 v[2:17], v[146:153], v[244:251], v[2:17], v1, v1 op_sel_hi:[0,0,0]
	ds_read_b128 v[142:145], v186 offset:2048
	ds_read_b128 v[130:133], v187 offset:6144
	ds_read_b128 v[210:213], v186 offset:4096
	ds_read_b128 v[134:137], v186 offset:6144
	v_max3_f32 v122, v122, v66, v67
	v_max3_f32 v122, v122, v68, v69
	v_max3_f32 v122, v122, v70, v71
	v_max3_f32 v122, v122, v72, v73
	v_max3_f32 v122, v122, v74, v75
	v_max3_f32 v122, v122, v76, v77
	v_max3_f32 v122, v122, v78, v79
	v_max3_f32 v122, v122, v80, v81
	v_mov_b32_e32 v123, v122
	s_nop 1
	v_permlane32_swap_b32_e32 v122, v123
	v_max_f32_e32 v123, v123, v123
	v_max_f32_e32 v122, v122, v122
	v_max_f32_e32 v122, v122, v123
	s_waitcnt lgkmcnt(3)
	v_mfma_scale_f32_32x32x64_f8f6f4 v[50:65], v[146:153], v[138:145], v[50:65], v1, v1 op_sel_hi:[0,0,0]
	v_max_f32_e32 v124, v128, v128
	v_sub_f32_e32 v123, v122, v128
	v_max_f32_e32 v122, v124, v122
	v_sub_f32_e32 v124, v128, v122
	v_mul_f32_e32 v124, 0x3dd53b94, v124
	v_exp_f32_e32 v124, v124
	v_cmp_ge_f32_e32 vcc, s61, v123
	s_cmp_eq_u64 vcc, exec
	s_cselect_b64 s[8:9], -1, 0
	s_waitcnt lgkmcnt(0)
	s_waitcnt vmcnt(3)
	v_cndmask_b32_e64 v205, v124, 1.0, s[8:9]
	v_cmp_gt_f32_e32 vcc, 1.0, v205
	v_mfma_scale_f32_32x32x64_f8f6f4 v[34:49], v[146:153], v[206:213], v[34:49], v1, v1 op_sel_hi:[0,0,0]
	s_waitcnt vmcnt(3)
	ds_write_b128 v193, v[156:159] offset:45056
	ds_write_b128 v195, v[160:163] offset:16384
	ds_write_b64 v197, v[172:173] offset:16384
	v_mfma_scale_f32_32x32x64_f8f6f4 v[18:33], v[146:153], v[130:137], v[18:33], v1, v1 op_sel_hi:[0,0,0]
	s_cbranch_vccz .LBB0_698
	s_and_saveexec_b64 s[56:57], s[6:7]
	ds_write_b32 v185, v205 offset:41088
	s_or_b64 exec, exec, s[56:57]
	s_waitcnt lgkmcnt(0)
	v_add_u32_e32 v123, v183, v184
	ds_read_b128 v[124:127], v123 offset:41184
	ds_read_b128 v[130:133], v123 offset:41152
	ds_read_b128 v[134:137], v123 offset:41120
	ds_read_b128 v[138:141], v123 offset:41088
	s_waitcnt lgkmcnt(3)
	v_pk_mul_f32 v[14:15], v[14:15], v[124:125]
	s_waitcnt lgkmcnt(2)
	v_pk_mul_f32 v[10:11], v[10:11], v[130:131]
	s_waitcnt lgkmcnt(1)
	v_pk_mul_f32 v[6:7], v[6:7], v[134:135]
	v_pk_mul_f32 v[16:17], v[16:17], v[126:127]
	v_pk_mul_f32 v[12:13], v[12:13], v[132:133]
	v_pk_mul_f32 v[8:9], v[8:9], v[136:137]
	s_waitcnt lgkmcnt(0)
	v_pk_mul_f32 v[4:5], v[4:5], v[140:141]
	v_pk_mul_f32 v[2:3], v[2:3], v[138:139]
	v_pk_mul_f32 v[62:63], v[62:63], v[124:125]
	v_pk_mul_f32 v[58:59], v[58:59], v[130:131]
	v_pk_mul_f32 v[54:55], v[54:55], v[134:135]
	v_pk_mul_f32 v[64:65], v[64:65], v[126:127]
	v_pk_mul_f32 v[60:61], v[60:61], v[132:133]
	v_pk_mul_f32 v[56:57], v[56:57], v[136:137]
	v_pk_mul_f32 v[52:53], v[52:53], v[140:141]
	v_pk_mul_f32 v[50:51], v[50:51], v[138:139]
	v_pk_mul_f32 v[46:47], v[46:47], v[124:125]
	v_pk_mul_f32 v[42:43], v[42:43], v[130:131]
	v_pk_mul_f32 v[38:39], v[38:39], v[134:135]
	v_pk_mul_f32 v[48:49], v[48:49], v[126:127]
	v_pk_mul_f32 v[44:45], v[44:45], v[132:133]
	v_pk_mul_f32 v[40:41], v[40:41], v[136:137]
	v_pk_mul_f32 v[36:37], v[36:37], v[140:141]
	v_pk_mul_f32 v[34:35], v[34:35], v[138:139]
	v_pk_mul_f32 v[30:31], v[30:31], v[124:125]
	v_pk_mul_f32 v[26:27], v[26:27], v[130:131]
	v_pk_mul_f32 v[22:23], v[22:23], v[134:135]
	v_pk_mul_f32 v[32:33], v[32:33], v[126:127]
	v_pk_mul_f32 v[28:29], v[28:29], v[132:133]
	v_pk_mul_f32 v[24:25], v[24:25], v[136:137]
	v_pk_mul_f32 v[20:21], v[20:21], v[140:141]
	v_pk_mul_f32 v[18:19], v[18:19], v[138:139]

.LBB0_700:
	s_waitcnt lgkmcnt(11)
	v_mfma_scale_f32_32x32x64_f8f6f4 v[82:97], v[66:73], v[114:121], 0, v1, v1 op_sel_hi:[0,0,0]
	v_add_f32_e32 v241, 0, v223
	v_add_f32_e32 v241, v224, v241
	v_add_f32_e32 v241, v215, v241
	v_add_f32_e32 v241, v217, v241
	v_add_f32_e32 v241, v221, v241
	v_add_f32_e32 v241, v222, v241
	v_add_f32_e32 v241, v219, v241
	v_add_f32_e32 v241, v220, v241
	s_waitcnt lgkmcnt(10)
	v_mfma_scale_f32_32x32x64_f8f6f4 v[66:81], v[74:81], v[114:121], 0, v1, v1 op_sel_hi:[0,0,0]
	v_add_f32_e32 v241, v216, v241
	v_add_f32_e32 v241, v218, v241
	v_add_f32_e32 v241, v209, v241
	v_add_f32_e32 v241, v210, v241
	v_add_f32_e32 v241, v213, v241
	v_add_f32_e32 v241, v214, v241
	v_add_f32_e32 v241, v211, v241
	v_add_f32_e32 v241, v212, v241
	s_waitcnt lgkmcnt(7)
	v_mfma_scale_f32_32x32x64_f8f6f4 v[82:97], v[146:153], v[106:113], v[82:97], v1, v1 op_sel_hi:[0,0,0]
	v_add_f32_e32 v241, v239, v241
	v_add_f32_e32 v241, v240, v241
	v_add_f32_e32 v241, v233, v241
	v_add_f32_e32 v241, v234, v241
	v_add_f32_e32 v241, v237, v241
	v_add_f32_e32 v241, v238, v241
	v_add_f32_e32 v241, v235, v241
	v_add_f32_e32 v241, v236, v241
	s_waitcnt lgkmcnt(6)
	v_mfma_scale_f32_32x32x64_f8f6f4 v[66:81], v[138:145], v[106:113], v[66:81], v1, v1 op_sel_hi:[0,0,0]
	v_add_f32_e32 v241, v231, v241
	v_add_f32_e32 v241, v232, v241
	v_add_f32_e32 v241, v225, v241
	v_add_f32_e32 v241, v226, v241
	v_add_f32_e32 v241, v229, v241
	v_add_f32_e32 v241, v230, v241
	v_add_f32_e32 v241, v227, v241
	v_add_f32_e32 v207, v228, v241
	v_mov_b32_e32 v208, v207
	s_nop 1
	v_permlane32_swap_b32_e32 v207, v208
	v_cvt_pk_fp8_f32 v138, v223, v224
	v_cvt_pk_fp8_f32 v142, v239, v240
	v_cvt_pk_fp8_f32 v139, v221, v222
	v_cvt_pk_fp8_f32 v143, v237, v238
	v_cvt_pk_fp8_f32 v140, v216, v218
	v_cvt_pk_fp8_f32 v144, v231, v232
	v_cvt_pk_fp8_f32 v141, v213, v214
	s_waitcnt lgkmcnt(3)
	v_mfma_scale_f32_32x32x64_f8f6f4 v[82:97], v[130:137], v[98:105], v[82:97], v1, v1 op_sel_hi:[0,0,0]
	v_cvt_pk_fp8_f32 v145, v229, v230
	v_cvt_pk_fp8_f32 v138, v215, v217 op_sel:[0,0,1]
	v_cvt_pk_fp8_f32 v142, v233, v234 op_sel:[0,0,1]
	v_cvt_pk_fp8_f32 v139, v219, v220 op_sel:[0,0,1]
	v_cvt_pk_fp8_f32 v143, v235, v236 op_sel:[0,0,1]
	v_cvt_pk_fp8_f32 v140, v209, v210 op_sel:[0,0,1]
	v_cvt_pk_fp8_f32 v144, v225, v226 op_sel:[0,0,1]
	v_cvt_pk_fp8_f32 v141, v211, v212 op_sel:[0,0,1]
	v_cvt_pk_fp8_f32 v145, v227, v228 op_sel:[0,0,1]
	s_waitcnt lgkmcnt(2)
	v_mfma_scale_f32_32x32x64_f8f6f4 v[66:81], v[122:129], v[98:105], v[66:81], v1, v1 op_sel_hi:[0,0,0]
	ds_read_b128 v[130:133], v187 offset:10240
	ds_read_b128 v[146:149], v187 offset:12288
	ds_read_b128 v[134:137], v186 offset:10240
	ds_read_b128 v[210:213], v187 offset:14336
	ds_read_b128 v[150:153], v186 offset:12288
	ds_read_b128 v[214:217], v186 offset:14336
	s_waitcnt lgkmcnt(6)
	v_mfma_scale_f32_32x32x64_f8f6f4 v[2:17], v[138:145], v[244:251], v[2:17], v1, v1 op_sel_hi:[0,0,0]
	s_nop 1
	v_max_f32_e32 v122, v83, v83
	v_max_f32_e32 v123, v82, v82
	v_max_f32_e32 v122, v123, v122
	v_max3_f32 v122, v122, v84, v85
	v_max3_f32 v122, v122, v86, v87
	v_max3_f32 v122, v122, v88, v89
	v_max3_f32 v122, v122, v90, v91
	v_max3_f32 v122, v122, v92, v93
	v_max3_f32 v122, v122, v94, v95
	v_max3_f32 v122, v122, v96, v97
	v_max3_f32 v122, v122, v66, v67
	v_max3_f32 v122, v122, v68, v69
	v_max3_f32 v122, v122, v70, v71
	v_max3_f32 v122, v122, v72, v73
	v_max3_f32 v122, v122, v74, v75
	s_waitcnt lgkmcnt(3)
	v_mfma_scale_f32_32x32x64_f8f6f4 v[50:65], v[138:145], v[130:137], v[50:65], v1, v1 op_sel_hi:[0,0,0]
	v_max3_f32 v122, v122, v76, v77
	v_max3_f32 v122, v122, v78, v79
	v_max3_f32 v122, v122, v80, v81
	v_mov_b32_e32 v123, v122
	s_nop 1
	v_permlane32_swap_b32_e32 v122, v123
	v_max_f32_e32 v123, v123, v123
	v_max_f32_e32 v122, v122, v122
	v_max_f32_e32 v122, v122, v123
	v_max_f32_e32 v124, v206, v206
	v_sub_f32_e32 v123, v122, v206
	v_max_f32_e32 v122, v124, v122
	v_sub_f32_e32 v124, v206, v122
	v_mul_f32_e32 v124, 0x3dd53b94, v124
	v_exp_f32_e32 v124, v124
	s_waitcnt lgkmcnt(0)
	v_mfma_scale_f32_32x32x64_f8f6f4 v[34:49], v[138:145], v[146:153], v[34:49], v1, v1 op_sel_hi:[0,0,0]
	v_cmp_ge_f32_e32 vcc, s61, v123
	s_cmp_eq_u64 vcc, exec
	s_cselect_b64 s[8:9], -1, 0
	s_waitcnt vmcnt(3)
	v_cndmask_b32_e64 v129, v124, 1.0, s[8:9]
	v_cmp_gt_f32_e32 vcc, 1.0, v129
	s_waitcnt vmcnt(2)
	ds_write_b128 v193, v[164:167]
	s_waitcnt vmcnt(1)
	ds_write_b128 v195, v[168:171] offset:28672
	s_waitcnt vmcnt(0)
	ds_write_b64 v197, v[174:175] offset:28672
	v_mfma_scale_f32_32x32x64_f8f6f4 v[18:33], v[138:145], v[210:217], v[18:33], v1, v1 op_sel_hi:[0,0,0]
	s_cbranch_vccz .LBB0_704
	s_and_saveexec_b64 s[58:59], s[6:7]
	ds_write_b32 v185, v129 offset:41088
	s_or_b64 exec, exec, s[58:59]
	s_waitcnt lgkmcnt(0)
	v_add_u32_e32 v123, v183, v184
	ds_read_b128 v[124:127], v123 offset:41184
	ds_read_b128 v[130:133], v123 offset:41152
	ds_read_b128 v[134:137], v123 offset:41120
	ds_read_b128 v[138:141], v123 offset:41088
	s_waitcnt lgkmcnt(3)
	v_pk_mul_f32 v[14:15], v[14:15], v[124:125]
	s_waitcnt lgkmcnt(2)
	v_pk_mul_f32 v[10:11], v[10:11], v[130:131]
	s_waitcnt lgkmcnt(1)
	v_pk_mul_f32 v[6:7], v[6:7], v[134:135]
	v_pk_mul_f32 v[16:17], v[16:17], v[126:127]
	v_pk_mul_f32 v[12:13], v[12:13], v[132:133]
	v_pk_mul_f32 v[8:9], v[8:9], v[136:137]
	s_waitcnt lgkmcnt(0)
	v_pk_mul_f32 v[4:5], v[4:5], v[140:141]
	v_pk_mul_f32 v[2:3], v[2:3], v[138:139]
	v_pk_mul_f32 v[62:63], v[62:63], v[124:125]
	v_pk_mul_f32 v[58:59], v[58:59], v[130:131]
	v_pk_mul_f32 v[54:55], v[54:55], v[134:135]
	v_pk_mul_f32 v[64:65], v[64:65], v[126:127]
	v_pk_mul_f32 v[60:61], v[60:61], v[132:133]
	v_pk_mul_f32 v[56:57], v[56:57], v[136:137]
	v_pk_mul_f32 v[52:53], v[52:53], v[140:141]
	v_pk_mul_f32 v[50:51], v[50:51], v[138:139]
	v_pk_mul_f32 v[46:47], v[46:47], v[124:125]
	v_pk_mul_f32 v[42:43], v[42:43], v[130:131]
	v_pk_mul_f32 v[38:39], v[38:39], v[134:135]
	v_pk_mul_f32 v[48:49], v[48:49], v[126:127]
	v_pk_mul_f32 v[44:45], v[44:45], v[132:133]
	v_pk_mul_f32 v[40:41], v[40:41], v[136:137]
	v_pk_mul_f32 v[36:37], v[36:37], v[140:141]
	v_pk_mul_f32 v[34:35], v[34:35], v[138:139]
	v_pk_mul_f32 v[30:31], v[30:31], v[124:125]
	v_pk_mul_f32 v[26:27], v[26:27], v[130:131]
	v_pk_mul_f32 v[22:23], v[22:23], v[134:135]
	v_pk_mul_f32 v[32:33], v[32:33], v[126:127]
	v_pk_mul_f32 v[28:29], v[28:29], v[132:133]
	v_pk_mul_f32 v[24:25], v[24:25], v[136:137]
	v_pk_mul_f32 v[20:21], v[20:21], v[140:141]
	v_pk_mul_f32 v[18:19], v[18:19], v[138:139]

.Latt3_c1:
	ds_read_b128 v[80:83], v196 offset:28672
	ds_read_b128 v[76:79], v194 offset:28672
	ds_read_b128 v[146:149], v194 offset:34816
	ds_read_b128 v[150:153], v196 offset:34816
	ds_read_b128 v[164:167], v198 offset:28672
	ds_read_b128 v[204:207], v198 offset:34816
	ds_read_b128 v[168:171], v199 offset:28672
	ds_read_b128 v[208:211], v199 offset:34816
	ds_read_b128 v[212:215], v201 offset:28672
	ds_read_b128 v[220:223], v201 offset:34816
	s_waitcnt lgkmcnt(8)
	v_mfma_scale_f32_32x32x64_f8f6f4 v[82:97], v[76:83], v[114:121], 0, v1, v1 op_sel_hi:[0,0,0]
	v_exp_f32_e32 v129, v70
	v_exp_f32_e32 v174, v71
	v_exp_f32_e32 v175, v68
	v_exp_f32_e32 v228, v69
	v_exp_f32_e32 v229, v66
	v_exp_f32_e32 v230, v67
	v_exp_f32_e32 v231, v74
	v_exp_f32_e32 v232, v75
	v_exp_f32_e32 v233, v72
	v_exp_f32_e32 v234, v73
	v_exp_f32_e32 v124, v124
	v_exp_f32_e32 v125, v125
	v_exp_f32_e32 v122, v122
	ds_read_b128 v[216:219], v200 offset:28672
	ds_read_b128 v[224:227], v200 offset:34816
	ds_read_b128 v[244:247], v189 offset:45056
	ds_read_b128 v[248:251], v190 offset:45056
	v_exp_f32_e32 v123, v123
	s_waitcnt lgkmcnt(10)
	v_mfma_scale_f32_32x32x64_f8f6f4 v[66:81], v[146:153], v[114:121], 0, v1, v1 op_sel_hi:[0,0,0]
	v_add_f32_e32 v146, 0, v144
	v_add_f32_e32 v146, v145, v146
	v_add_f32_e32 v146, v136, v146
	v_add_f32_e32 v146, v138, v146
	v_add_f32_e32 v146, v142, v146
	v_add_f32_e32 v146, v143, v146
	v_add_f32_e32 v146, v140, v146
	v_add_f32_e32 v146, v141, v146
	v_add_f32_e32 v146, v137, v146
	v_add_f32_e32 v146, v139, v146
	v_add_f32_e32 v146, v130, v146
	v_add_f32_e32 v146, v131, v146
	v_add_f32_e32 v146, v134, v146
	v_add_f32_e32 v146, v135, v146
	v_add_f32_e32 v146, v132, v146
	s_waitcnt lgkmcnt(7)
	v_mfma_scale_f32_32x32x64_f8f6f4 v[82:97], v[164:171], v[106:113], v[82:97], v1, v1 op_sel_hi:[0,0,0]
	v_add_f32_e32 v146, v133, v146
	v_add_f32_e32 v146, v124, v146
	v_add_f32_e32 v146, v125, v146
	v_add_f32_e32 v146, v122, v146
	v_add_f32_e32 v146, v123, v146
	v_add_f32_e32 v146, v129, v146
	v_add_f32_e32 v146, v174, v146
	v_add_f32_e32 v146, v175, v146
	v_add_f32_e32 v146, v228, v146
	v_add_f32_e32 v146, v229, v146
	v_add_f32_e32 v146, v230, v146
	v_exp_f32_e32 v126, v126
	v_add_f32_e32 v146, v231, v146
	v_exp_f32_e32 v127, v127
	v_add_f32_e32 v146, v232, v146
	s_waitcnt lgkmcnt(6)
	v_mfma_scale_f32_32x32x64_f8f6f4 v[66:81], v[204:211], v[106:113], v[66:81], v1, v1 op_sel_hi:[0,0,0]
	v_add_f32_e32 v146, v233, v146
	v_add_f32_e32 v146, v234, v146
	v_add_f32_e32 v146, v126, v146
	v_add_f32_e32 v203, v127, v146
	v_cvt_pk_fp8_f32 v146, v144, v145
	v_cvt_pk_fp8_f32 v150, v124, v125
	v_cvt_pk_fp8_f32 v147, v142, v143
	s_waitcnt lgkmcnt(3)
	v_mfma_scale_f32_32x32x64_f8f6f4 v[82:97], v[212:219], v[98:105], v[82:97], v1, v1 op_sel_hi:[0,0,0]
	v_cvt_pk_fp8_f32 v151, v129, v174
	v_cvt_pk_fp8_f32 v148, v137, v139
	v_cvt_pk_fp8_f32 v152, v229, v230
	v_cvt_pk_fp8_f32 v149, v134, v135
	v_cvt_pk_fp8_f32 v153, v233, v234
	v_mov_b32_e32 v204, v203
	s_nop 1
	v_permlane32_swap_b32_e32 v203, v204
	v_cvt_pk_fp8_f32 v146, v136, v138 op_sel:[0,0,1]
	v_cvt_pk_fp8_f32 v150, v122, v123 op_sel:[0,0,1]
	v_cvt_pk_fp8_f32 v147, v140, v141 op_sel:[0,0,1]
	v_cvt_pk_fp8_f32 v151, v175, v228 op_sel:[0,0,1]
	v_cvt_pk_fp8_f32 v148, v130, v131 op_sel:[0,0,1]
	v_cvt_pk_fp8_f32 v152, v231, v232 op_sel:[0,0,1]
	v_cvt_pk_fp8_f32 v149, v132, v133 op_sel:[0,0,1]
	s_waitcnt lgkmcnt(2)
	v_mfma_scale_f32_32x32x64_f8f6f4 v[66:81], v[220:227], v[98:105], v[66:81], v1, v1 op_sel_hi:[0,0,0]
	v_cvt_pk_fp8_f32 v153, v126, v127 op_sel:[0,0,1]
	s_add_i32 s8, s11, 0xffffe000
	s_add_i32 s9, s72, 0xffffd000
	buffer_load_dwordx4 v[164:167], v191, s[40:43], s8 offen
	buffer_load_dwordx4 v[168:171], v191, s[36:39], s9 offen
	buffer_load_dwordx2 v[174:175], v192, s[36:39], s9 offen
	v_max_f32_e32 v122, v83, v83
	v_max_f32_e32 v123, v82, v82
	v_max_f32_e32 v122, v123, v122
	v_max3_f32 v122, v122, v84, v85
	v_max3_f32 v122, v122, v86, v87
	v_max3_f32 v122, v122, v88, v89
	v_max3_f32 v122, v122, v90, v91
	ds_read_b128 v[138:141], v187 offset:47104
	ds_read_b128 v[206:209], v187 offset:49152
	v_max3_f32 v122, v122, v92, v93
	v_max3_f32 v122, v122, v94, v95
	v_max3_f32 v122, v122, v96, v97
	s_waitcnt lgkmcnt(2)
	v_mfma_scale_f32_32x32x64_f8f6f4 v[2:17], v[146:153], v[244:251], v[2:17], v1, v1 op_sel_hi:[0,0,0]
	ds_read_b128 v[142:145], v186 offset:47104
	ds_read_b128 v[130:133], v187 offset:51200
	ds_read_b128 v[210:213], v186 offset:49152
	ds_read_b128 v[134:137], v186 offset:51200
	v_max3_f32 v122, v122, v66, v67
	v_max3_f32 v122, v122, v68, v69
	v_max3_f32 v122, v122, v70, v71
	v_max3_f32 v122, v122, v72, v73
	v_max3_f32 v122, v122, v74, v75
	v_max3_f32 v122, v122, v76, v77
	v_max3_f32 v122, v122, v78, v79
	v_max3_f32 v122, v122, v80, v81
	v_mov_b32_e32 v123, v122
	s_nop 1
	v_permlane32_swap_b32_e32 v122, v123
	v_max_f32_e32 v123, v123, v123
	v_max_f32_e32 v122, v122, v122
	v_max_f32_e32 v122, v122, v123
	s_waitcnt lgkmcnt(3)
	v_mfma_scale_f32_32x32x64_f8f6f4 v[50:65], v[146:153], v[138:145], v[50:65], v1, v1 op_sel_hi:[0,0,0]
	v_max_f32_e32 v124, v128, v128
	v_sub_f32_e32 v123, v122, v128
	v_max_f32_e32 v122, v124, v122
	v_sub_f32_e32 v124, v128, v122
	v_mul_f32_e32 v124, 0x3dd53b94, v124
	v_exp_f32_e32 v124, v124
	v_cmp_ge_f32_e32 vcc, s61, v123
	s_cmp_eq_u64 vcc, exec
	s_cselect_b64 s[8:9], -1, 0
	s_waitcnt lgkmcnt(0)
	s_waitcnt vmcnt(3)
	v_cndmask_b32_e64 v205, v124, 1.0, s[8:9]
	v_cmp_gt_f32_e32 vcc, 1.0, v205
	v_mfma_scale_f32_32x32x64_f8f6f4 v[34:49], v[146:153], v[206:213], v[34:49], v1, v1 op_sel_hi:[0,0,0]
	s_waitcnt vmcnt(3)
	ds_write_b128 v193, v[156:159] offset:8192
	ds_write_b128 v195, v[160:163] offset:16384
	ds_write_b64 v197, v[172:173] offset:16384
	v_mfma_scale_f32_32x32x64_f8f6f4 v[18:33], v[146:153], v[130:137], v[18:33], v1, v1 op_sel_hi:[0,0,0]
	s_cbranch_vccz .Latt3_c1_698
	s_and_saveexec_b64 s[56:57], s[6:7]
	ds_write_b32 v185, v205 offset:41088
	s_or_b64 exec, exec, s[56:57]
	s_waitcnt lgkmcnt(0)
	v_add_u32_e32 v123, v183, v184
	ds_read_b128 v[124:127], v123 offset:41184
	ds_read_b128 v[130:133], v123 offset:41152
	ds_read_b128 v[134:137], v123 offset:41120
	ds_read_b128 v[138:141], v123 offset:41088
	s_waitcnt lgkmcnt(3)
	v_pk_mul_f32 v[14:15], v[14:15], v[124:125]
	s_waitcnt lgkmcnt(2)
	v_pk_mul_f32 v[10:11], v[10:11], v[130:131]
	s_waitcnt lgkmcnt(1)
	v_pk_mul_f32 v[6:7], v[6:7], v[134:135]
	v_pk_mul_f32 v[16:17], v[16:17], v[126:127]
	v_pk_mul_f32 v[12:13], v[12:13], v[132:133]
	v_pk_mul_f32 v[8:9], v[8:9], v[136:137]
	s_waitcnt lgkmcnt(0)
	v_pk_mul_f32 v[4:5], v[4:5], v[140:141]
	v_pk_mul_f32 v[2:3], v[2:3], v[138:139]
	v_pk_mul_f32 v[62:63], v[62:63], v[124:125]
	v_pk_mul_f32 v[58:59], v[58:59], v[130:131]
	v_pk_mul_f32 v[54:55], v[54:55], v[134:135]
	v_pk_mul_f32 v[64:65], v[64:65], v[126:127]
	v_pk_mul_f32 v[60:61], v[60:61], v[132:133]
	v_pk_mul_f32 v[56:57], v[56:57], v[136:137]
	v_pk_mul_f32 v[52:53], v[52:53], v[140:141]
	v_pk_mul_f32 v[50:51], v[50:51], v[138:139]
	v_pk_mul_f32 v[46:47], v[46:47], v[124:125]
	v_pk_mul_f32 v[42:43], v[42:43], v[130:131]
	v_pk_mul_f32 v[38:39], v[38:39], v[134:135]
	v_pk_mul_f32 v[48:49], v[48:49], v[126:127]
	v_pk_mul_f32 v[44:45], v[44:45], v[132:133]
	v_pk_mul_f32 v[40:41], v[40:41], v[136:137]
	v_pk_mul_f32 v[36:37], v[36:37], v[140:141]
	v_pk_mul_f32 v[34:35], v[34:35], v[138:139]
	v_pk_mul_f32 v[30:31], v[30:31], v[124:125]
	v_pk_mul_f32 v[26:27], v[26:27], v[130:131]
	v_pk_mul_f32 v[22:23], v[22:23], v[134:135]
	v_pk_mul_f32 v[32:33], v[32:33], v[126:127]
	v_pk_mul_f32 v[28:29], v[28:29], v[132:133]
	v_pk_mul_f32 v[24:25], v[24:25], v[136:137]
	v_pk_mul_f32 v[20:21], v[20:21], v[140:141]
	v_pk_mul_f32 v[18:19], v[18:19], v[138:139]
.Latt3_c1_698:
	v_cndmask_b32_e64 v206, v122, v128, s[8:9]
	v_fma_f32 v207, v206, s62, 4.0
	v_fmamk_f32 v122, v82, 0x3dd53b94, v207
	v_fmamk_f32 v123, v83, 0x3dd53b94, v207
	v_fmamk_f32 v124, v84, 0x3dd53b94, v207
	v_fmamk_f32 v125, v85, 0x3dd53b94, v207
	v_fmamk_f32 v126, v86, 0x3dd53b94, v207
	v_fmamk_f32 v127, v87, 0x3dd53b94, v207
	v_fmamk_f32 v128, v88, 0x3dd53b94, v207
	v_fmamk_f32 v129, v89, 0x3dd53b94, v207
	v_fmamk_f32 v130, v90, 0x3dd53b94, v207
	v_fmamk_f32 v131, v91, 0x3dd53b94, v207
	v_fmamk_f32 v132, v92, 0x3dd53b94, v207
	v_fmamk_f32 v133, v93, 0x3dd53b94, v207
	v_fmamk_f32 v134, v94, 0x3dd53b94, v207
	v_fmamk_f32 v95, v95, 0x3dd53b94, v207
	v_fmamk_f32 v96, v96, 0x3dd53b94, v207
	v_fmamk_f32 v97, v97, 0x3dd53b94, v207
	v_exp_f32_e32 v223, v122
	v_exp_f32_e32 v224, v123
	v_exp_f32_e32 v215, v124
	v_exp_f32_e32 v217, v125
	v_exp_f32_e32 v221, v126
	v_exp_f32_e32 v222, v127
	v_exp_f32_e32 v219, v128
	v_exp_f32_e32 v220, v129
	v_exp_f32_e32 v216, v130
	v_exp_f32_e32 v218, v131
	v_exp_f32_e32 v209, v132
	v_exp_f32_e32 v210, v133
	v_exp_f32_e32 v213, v134
	v_exp_f32_e32 v214, v95
	v_exp_f32_e32 v211, v96
	v_exp_f32_e32 v212, v97
	v_fmamk_f32 v82, v66, 0x3dd53b94, v207
	v_fmamk_f32 v83, v67, 0x3dd53b94, v207
	v_fmamk_f32 v84, v68, 0x3dd53b94, v207
	v_fmamk_f32 v85, v69, 0x3dd53b94, v207
	v_fmamk_f32 v86, v70, 0x3dd53b94, v207
	v_fmamk_f32 v87, v71, 0x3dd53b94, v207
	v_fmamk_f32 v88, v72, 0x3dd53b94, v207
	v_fmamk_f32 v89, v73, 0x3dd53b94, v207
	v_fmamk_f32 v90, v74, 0x3dd53b94, v207
	v_fmamk_f32 v91, v75, 0x3dd53b94, v207
	v_fmamk_f32 v92, v76, 0x3dd53b94, v207
	v_fmamk_f32 v93, v77, 0x3dd53b94, v207
	v_fmamk_f32 v94, v78, 0x3dd53b94, v207
	v_fmamk_f32 v95, v79, 0x3dd53b94, v207
	v_fmamk_f32 v96, v80, 0x3dd53b94, v207
	v_fmac_f32_e32 v207, 0x3dd53b94, v81
	s_waitcnt lgkmcnt(0)
	s_barrier
	ds_read_b128 v[66:69], v194 offset:16384
	ds_read_b128 v[74:77], v194 offset:22528
	ds_read_b128 v[70:73], v196 offset:16384
	ds_read_b128 v[78:81], v196 offset:22528
	ds_read_b128 v[146:149], v198 offset:16384
	ds_read_b128 v[138:141], v198 offset:22528
	ds_read_b128 v[150:153], v199 offset:16384
	ds_read_b128 v[142:145], v199 offset:22528
	ds_read_b128 v[130:133], v201 offset:16384
	ds_read_b128 v[122:125], v201 offset:22528
	ds_read_b128 v[134:137], v200 offset:16384
	ds_read_b128 v[126:129], v200 offset:22528
	ds_read_b128 v[244:247], v189
	ds_read_b128 v[248:251], v190
	v_exp_f32_e32 v239, v82
	v_exp_f32_e32 v240, v83
	v_exp_f32_e32 v233, v84
	v_exp_f32_e32 v234, v85
	v_exp_f32_e32 v237, v86
	v_exp_f32_e32 v238, v87
	v_exp_f32_e32 v235, v88
	v_exp_f32_e32 v236, v89
	v_exp_f32_e32 v231, v90
	v_exp_f32_e32 v232, v91
	v_exp_f32_e32 v225, v92
	v_exp_f32_e32 v226, v93
	v_exp_f32_e32 v229, v94
	v_exp_f32_e32 v230, v95
	v_exp_f32_e32 v227, v96
	v_exp_f32_e32 v228, v207
	s_cmpk_gt_u32 s73, 0x80
	s_cselect_b64 s[56:57], -1, 0
	s_and_b64 vcc, exec, s[56:57]
	s_cbranch_vccnz .Latt3_c1_700
	buffer_load_dwordx4 v[156:159], v191, s[40:43], s11 offen
	buffer_load_dwordx4 v[160:163], v191, s[36:39], s72 offen
	buffer_load_dwordx2 v[172:173], v192, s[36:39], s72 offen
.Latt3_c1_700:
	s_waitcnt lgkmcnt(11)
	v_mfma_scale_f32_32x32x64_f8f6f4 v[82:97], v[66:73], v[114:121], 0, v1, v1 op_sel_hi:[0,0,0]
	v_add_f32_e32 v241, 0, v223
	v_add_f32_e32 v241, v224, v241
	v_add_f32_e32 v241, v215, v241
	v_add_f32_e32 v241, v217, v241
	v_add_f32_e32 v241, v221, v241
	v_add_f32_e32 v241, v222, v241
	v_add_f32_e32 v241, v219, v241
	v_add_f32_e32 v241, v220, v241
	s_waitcnt lgkmcnt(10)
	v_mfma_scale_f32_32x32x64_f8f6f4 v[66:81], v[74:81], v[114:121], 0, v1, v1 op_sel_hi:[0,0,0]
	v_add_f32_e32 v241, v216, v241
	v_add_f32_e32 v241, v218, v241
	v_add_f32_e32 v241, v209, v241
	v_add_f32_e32 v241, v210, v241
	v_add_f32_e32 v241, v213, v241
	v_add_f32_e32 v241, v214, v241
	v_add_f32_e32 v241, v211, v241
	v_add_f32_e32 v241, v212, v241
	s_waitcnt lgkmcnt(7)
	v_mfma_scale_f32_32x32x64_f8f6f4 v[82:97], v[146:153], v[106:113], v[82:97], v1, v1 op_sel_hi:[0,0,0]
	v_add_f32_e32 v241, v239, v241
	v_add_f32_e32 v241, v240, v241
	v_add_f32_e32 v241, v233, v241
	v_add_f32_e32 v241, v234, v241
	v_add_f32_e32 v241, v237, v241
	v_add_f32_e32 v241, v238, v241
	v_add_f32_e32 v241, v235, v241
	v_add_f32_e32 v241, v236, v241
	s_waitcnt lgkmcnt(6)
	v_mfma_scale_f32_32x32x64_f8f6f4 v[66:81], v[138:145], v[106:113], v[66:81], v1, v1 op_sel_hi:[0,0,0]
	v_add_f32_e32 v241, v231, v241
	v_add_f32_e32 v241, v232, v241
	v_add_f32_e32 v241, v225, v241
	v_add_f32_e32 v241, v226, v241
	v_add_f32_e32 v241, v229, v241
	v_add_f32_e32 v241, v230, v241
	v_add_f32_e32 v241, v227, v241
	v_add_f32_e32 v207, v228, v241
	v_mov_b32_e32 v208, v207
	s_nop 1
	v_permlane32_swap_b32_e32 v207, v208
	v_cvt_pk_fp8_f32 v138, v223, v224
	v_cvt_pk_fp8_f32 v142, v239, v240
	v_cvt_pk_fp8_f32 v139, v221, v222
	v_cvt_pk_fp8_f32 v143, v237, v238
	v_cvt_pk_fp8_f32 v140, v216, v218
	v_cvt_pk_fp8_f32 v144, v231, v232
	v_cvt_pk_fp8_f32 v141, v213, v214
	s_waitcnt lgkmcnt(3)
	v_mfma_scale_f32_32x32x64_f8f6f4 v[82:97], v[130:137], v[98:105], v[82:97], v1, v1 op_sel_hi:[0,0,0]
	v_cvt_pk_fp8_f32 v145, v229, v230
	v_cvt_pk_fp8_f32 v138, v215, v217 op_sel:[0,0,1]
	v_cvt_pk_fp8_f32 v142, v233, v234 op_sel:[0,0,1]
	v_cvt_pk_fp8_f32 v139, v219, v220 op_sel:[0,0,1]
	v_cvt_pk_fp8_f32 v143, v235, v236 op_sel:[0,0,1]
	v_cvt_pk_fp8_f32 v140, v209, v210 op_sel:[0,0,1]
	v_cvt_pk_fp8_f32 v144, v225, v226 op_sel:[0,0,1]
	v_cvt_pk_fp8_f32 v141, v211, v212 op_sel:[0,0,1]
	v_cvt_pk_fp8_f32 v145, v227, v228 op_sel:[0,0,1]
	s_waitcnt lgkmcnt(2)
	v_mfma_scale_f32_32x32x64_f8f6f4 v[66:81], v[122:129], v[98:105], v[66:81], v1, v1 op_sel_hi:[0,0,0]
	ds_read_b128 v[130:133], v187 offset:2048
	ds_read_b128 v[146:149], v187 offset:4096
	ds_read_b128 v[134:137], v186 offset:2048
	ds_read_b128 v[210:213], v187 offset:6144
	ds_read_b128 v[150:153], v186 offset:4096
	ds_read_b128 v[214:217], v186 offset:6144
	s_waitcnt lgkmcnt(6)
	v_mfma_scale_f32_32x32x64_f8f6f4 v[2:17], v[138:145], v[244:251], v[2:17], v1, v1 op_sel_hi:[0,0,0]
	s_nop 1
	v_max_f32_e32 v122, v83, v83
	v_max_f32_e32 v123, v82, v82
	v_max_f32_e32 v122, v123, v122
	v_max3_f32 v122, v122, v84, v85
	v_max3_f32 v122, v122, v86, v87
	v_max3_f32 v122, v122, v88, v89
	v_max3_f32 v122, v122, v90, v91
	v_max3_f32 v122, v122, v92, v93
	v_max3_f32 v122, v122, v94, v95
	v_max3_f32 v122, v122, v96, v97
	v_max3_f32 v122, v122, v66, v67
	v_max3_f32 v122, v122, v68, v69
	v_max3_f32 v122, v122, v70, v71
	v_max3_f32 v122, v122, v72, v73
	v_max3_f32 v122, v122, v74, v75
	s_waitcnt lgkmcnt(3)
	v_mfma_scale_f32_32x32x64_f8f6f4 v[50:65], v[138:145], v[130:137], v[50:65], v1, v1 op_sel_hi:[0,0,0]
	v_max3_f32 v122, v122, v76, v77
	v_max3_f32 v122, v122, v78, v79
	v_max3_f32 v122, v122, v80, v81
	v_mov_b32_e32 v123, v122
	s_nop 1
	v_permlane32_swap_b32_e32 v122, v123
	v_max_f32_e32 v123, v123, v123
	v_max_f32_e32 v122, v122, v122
	v_max_f32_e32 v122, v122, v123
	v_max_f32_e32 v124, v206, v206
	v_sub_f32_e32 v123, v122, v206
	v_max_f32_e32 v122, v124, v122
	v_sub_f32_e32 v124, v206, v122
	v_mul_f32_e32 v124, 0x3dd53b94, v124
	v_exp_f32_e32 v124, v124
	s_waitcnt lgkmcnt(0)
	v_mfma_scale_f32_32x32x64_f8f6f4 v[34:49], v[138:145], v[146:153], v[34:49], v1, v1 op_sel_hi:[0,0,0]
	v_cmp_ge_f32_e32 vcc, s61, v123
	s_cmp_eq_u64 vcc, exec
	s_cselect_b64 s[8:9], -1, 0
	s_waitcnt vmcnt(3)
	v_cndmask_b32_e64 v129, v124, 1.0, s[8:9]
	v_cmp_gt_f32_e32 vcc, 1.0, v129
	s_waitcnt vmcnt(2)
	ds_write_b128 v193, v[164:167] offset:45056
	s_waitcnt vmcnt(1)
	ds_write_b128 v195, v[168:171] offset:28672
	s_waitcnt vmcnt(0)
	ds_write_b64 v197, v[174:175] offset:28672
	v_mfma_scale_f32_32x32x64_f8f6f4 v[18:33], v[138:145], v[210:217], v[18:33], v1, v1 op_sel_hi:[0,0,0]
	s_cbranch_vccz .Latt3_c1_704
	s_and_saveexec_b64 s[58:59], s[6:7]
	ds_write_b32 v185, v129 offset:41088
	s_or_b64 exec, exec, s[58:59]
	s_waitcnt lgkmcnt(0)
	v_add_u32_e32 v123, v183, v184
	ds_read_b128 v[124:127], v123 offset:41184
	ds_read_b128 v[130:133], v123 offset:41152
	ds_read_b128 v[134:137], v123 offset:41120
	ds_read_b128 v[138:141], v123 offset:41088
	s_waitcnt lgkmcnt(3)
	v_pk_mul_f32 v[14:15], v[14:15], v[124:125]
	s_waitcnt lgkmcnt(2)
	v_pk_mul_f32 v[10:11], v[10:11], v[130:131]
	s_waitcnt lgkmcnt(1)
	v_pk_mul_f32 v[6:7], v[6:7], v[134:135]
	v_pk_mul_f32 v[16:17], v[16:17], v[126:127]
	v_pk_mul_f32 v[12:13], v[12:13], v[132:133]
	v_pk_mul_f32 v[8:9], v[8:9], v[136:137]
	s_waitcnt lgkmcnt(0)
	v_pk_mul_f32 v[4:5], v[4:5], v[140:141]
	v_pk_mul_f32 v[2:3], v[2:3], v[138:139]
	v_pk_mul_f32 v[62:63], v[62:63], v[124:125]
	v_pk_mul_f32 v[58:59], v[58:59], v[130:131]
	v_pk_mul_f32 v[54:55], v[54:55], v[134:135]
	v_pk_mul_f32 v[64:65], v[64:65], v[126:127]
	v_pk_mul_f32 v[60:61], v[60:61], v[132:133]
	v_pk_mul_f32 v[56:57], v[56:57], v[136:137]
	v_pk_mul_f32 v[52:53], v[52:53], v[140:141]
	v_pk_mul_f32 v[50:51], v[50:51], v[138:139]
	v_pk_mul_f32 v[46:47], v[46:47], v[124:125]
	v_pk_mul_f32 v[42:43], v[42:43], v[130:131]
	v_pk_mul_f32 v[38:39], v[38:39], v[134:135]
	v_pk_mul_f32 v[48:49], v[48:49], v[126:127]
	v_pk_mul_f32 v[44:45], v[44:45], v[132:133]
	v_pk_mul_f32 v[40:41], v[40:41], v[136:137]
	v_pk_mul_f32 v[36:37], v[36:37], v[140:141]
	v_pk_mul_f32 v[34:35], v[34:35], v[138:139]
	v_pk_mul_f32 v[30:31], v[30:31], v[124:125]
	v_pk_mul_f32 v[26:27], v[26:27], v[130:131]
	v_pk_mul_f32 v[22:23], v[22:23], v[134:135]
	v_pk_mul_f32 v[32:33], v[32:33], v[126:127]
	v_pk_mul_f32 v[28:29], v[28:29], v[132:133]
	v_pk_mul_f32 v[24:25], v[24:25], v[136:137]
	v_pk_mul_f32 v[20:21], v[20:21], v[140:141]
	v_pk_mul_f32 v[18:19], v[18:19], v[138:139]

.Latt3_c2:
	ds_read_b128 v[80:83], v196 offset:28672
	ds_read_b128 v[76:79], v194 offset:28672
	ds_read_b128 v[146:149], v194 offset:34816
	ds_read_b128 v[150:153], v196 offset:34816
	ds_read_b128 v[164:167], v198 offset:28672
	ds_read_b128 v[204:207], v198 offset:34816
	ds_read_b128 v[168:171], v199 offset:28672
	ds_read_b128 v[208:211], v199 offset:34816
	ds_read_b128 v[212:215], v201 offset:28672
	ds_read_b128 v[220:223], v201 offset:34816
	s_waitcnt lgkmcnt(8)
	v_mfma_scale_f32_32x32x64_f8f6f4 v[82:97], v[76:83], v[114:121], 0, v1, v1 op_sel_hi:[0,0,0]
	v_exp_f32_e32 v129, v70
	v_exp_f32_e32 v174, v71
	v_exp_f32_e32 v175, v68
	v_exp_f32_e32 v228, v69
	v_exp_f32_e32 v229, v66
	v_exp_f32_e32 v230, v67
	v_exp_f32_e32 v231, v74
	v_exp_f32_e32 v232, v75
	v_exp_f32_e32 v233, v72
	v_exp_f32_e32 v234, v73
	v_exp_f32_e32 v124, v124
	v_exp_f32_e32 v125, v125
	v_exp_f32_e32 v122, v122
	ds_read_b128 v[216:219], v200 offset:28672
	ds_read_b128 v[224:227], v200 offset:34816
	ds_read_b128 v[244:247], v189 offset:8192
	ds_read_b128 v[248:251], v190 offset:8192
	v_exp_f32_e32 v123, v123
	s_waitcnt lgkmcnt(10)
	v_mfma_scale_f32_32x32x64_f8f6f4 v[66:81], v[146:153], v[114:121], 0, v1, v1 op_sel_hi:[0,0,0]
	v_add_f32_e32 v146, 0, v144
	v_add_f32_e32 v146, v145, v146
	v_add_f32_e32 v146, v136, v146
	v_add_f32_e32 v146, v138, v146
	v_add_f32_e32 v146, v142, v146
	v_add_f32_e32 v146, v143, v146
	v_add_f32_e32 v146, v140, v146
	v_add_f32_e32 v146, v141, v146
	v_add_f32_e32 v146, v137, v146
	v_add_f32_e32 v146, v139, v146
	v_add_f32_e32 v146, v130, v146
	v_add_f32_e32 v146, v131, v146
	v_add_f32_e32 v146, v134, v146
	v_add_f32_e32 v146, v135, v146
	v_add_f32_e32 v146, v132, v146
	s_waitcnt lgkmcnt(7)
	v_mfma_scale_f32_32x32x64_f8f6f4 v[82:97], v[164:171], v[106:113], v[82:97], v1, v1 op_sel_hi:[0,0,0]
	v_add_f32_e32 v146, v133, v146
	v_add_f32_e32 v146, v124, v146
	v_add_f32_e32 v146, v125, v146
	v_add_f32_e32 v146, v122, v146
	v_add_f32_e32 v146, v123, v146
	v_add_f32_e32 v146, v129, v146
	v_add_f32_e32 v146, v174, v146
	v_add_f32_e32 v146, v175, v146
	v_add_f32_e32 v146, v228, v146
	v_add_f32_e32 v146, v229, v146
	v_add_f32_e32 v146, v230, v146
	v_exp_f32_e32 v126, v126
	v_add_f32_e32 v146, v231, v146
	v_exp_f32_e32 v127, v127
	v_add_f32_e32 v146, v232, v146
	s_waitcnt lgkmcnt(6)
	v_mfma_scale_f32_32x32x64_f8f6f4 v[66:81], v[204:211], v[106:113], v[66:81], v1, v1 op_sel_hi:[0,0,0]
	v_add_f32_e32 v146, v233, v146
	v_add_f32_e32 v146, v234, v146
	v_add_f32_e32 v146, v126, v146
	v_add_f32_e32 v203, v127, v146
	v_cvt_pk_fp8_f32 v146, v144, v145
	v_cvt_pk_fp8_f32 v150, v124, v125
	v_cvt_pk_fp8_f32 v147, v142, v143
	s_waitcnt lgkmcnt(3)
	v_mfma_scale_f32_32x32x64_f8f6f4 v[82:97], v[212:219], v[98:105], v[82:97], v1, v1 op_sel_hi:[0,0,0]
	v_cvt_pk_fp8_f32 v151, v129, v174
	v_cvt_pk_fp8_f32 v148, v137, v139
	v_cvt_pk_fp8_f32 v152, v229, v230
	v_cvt_pk_fp8_f32 v149, v134, v135
	v_cvt_pk_fp8_f32 v153, v233, v234
	v_mov_b32_e32 v204, v203
	s_nop 1
	v_permlane32_swap_b32_e32 v203, v204
	v_cvt_pk_fp8_f32 v146, v136, v138 op_sel:[0,0,1]
	v_cvt_pk_fp8_f32 v150, v122, v123 op_sel:[0,0,1]
	v_cvt_pk_fp8_f32 v147, v140, v141 op_sel:[0,0,1]
	v_cvt_pk_fp8_f32 v151, v175, v228 op_sel:[0,0,1]
	v_cvt_pk_fp8_f32 v148, v130, v131 op_sel:[0,0,1]
	v_cvt_pk_fp8_f32 v152, v231, v232 op_sel:[0,0,1]
	v_cvt_pk_fp8_f32 v149, v132, v133 op_sel:[0,0,1]
	s_waitcnt lgkmcnt(2)
	v_mfma_scale_f32_32x32x64_f8f6f4 v[66:81], v[220:227], v[98:105], v[66:81], v1, v1 op_sel_hi:[0,0,0]
	v_cvt_pk_fp8_f32 v153, v126, v127 op_sel:[0,0,1]
	s_add_i32 s8, s11, 0xffffe000
	s_add_i32 s9, s72, 0xffffd000
	buffer_load_dwordx4 v[164:167], v191, s[40:43], s8 offen
	buffer_load_dwordx4 v[168:171], v191, s[36:39], s9 offen
	buffer_load_dwordx2 v[174:175], v192, s[36:39], s9 offen
	v_max_f32_e32 v122, v83, v83
	v_max_f32_e32 v123, v82, v82
	v_max_f32_e32 v122, v123, v122
	v_max3_f32 v122, v122, v84, v85
	v_max3_f32 v122, v122, v86, v87
	v_max3_f32 v122, v122, v88, v89
	v_max3_f32 v122, v122, v90, v91
	ds_read_b128 v[138:141], v187 offset:10240
	ds_read_b128 v[206:209], v187 offset:12288
	v_max3_f32 v122, v122, v92, v93
	v_max3_f32 v122, v122, v94, v95
	v_max3_f32 v122, v122, v96, v97
	s_waitcnt lgkmcnt(2)
	v_mfma_scale_f32_32x32x64_f8f6f4 v[2:17], v[146:153], v[244:251], v[2:17], v1, v1 op_sel_hi:[0,0,0]
	ds_read_b128 v[142:145], v186 offset:10240
	ds_read_b128 v[130:133], v187 offset:14336
	ds_read_b128 v[210:213], v186 offset:12288
	ds_read_b128 v[134:137], v186 offset:14336
	v_max3_f32 v122, v122, v66, v67
	v_max3_f32 v122, v122, v68, v69
	v_max3_f32 v122, v122, v70, v71
	v_max3_f32 v122, v122, v72, v73
	v_max3_f32 v122, v122, v74, v75
	v_max3_f32 v122, v122, v76, v77
	v_max3_f32 v122, v122, v78, v79
	v_max3_f32 v122, v122, v80, v81
	v_mov_b32_e32 v123, v122
	s_nop 1
	v_permlane32_swap_b32_e32 v122, v123
	v_max_f32_e32 v123, v123, v123
	v_max_f32_e32 v122, v122, v122
	v_max_f32_e32 v122, v122, v123
	s_waitcnt lgkmcnt(3)
	v_mfma_scale_f32_32x32x64_f8f6f4 v[50:65], v[146:153], v[138:145], v[50:65], v1, v1 op_sel_hi:[0,0,0]
	v_max_f32_e32 v124, v128, v128
	v_sub_f32_e32 v123, v122, v128
	v_max_f32_e32 v122, v124, v122
	v_sub_f32_e32 v124, v128, v122
	v_mul_f32_e32 v124, 0x3dd53b94, v124
	v_exp_f32_e32 v124, v124
	v_cmp_ge_f32_e32 vcc, s61, v123
	s_cmp_eq_u64 vcc, exec
	s_cselect_b64 s[8:9], -1, 0
	s_waitcnt lgkmcnt(0)
	s_waitcnt vmcnt(3)
	v_cndmask_b32_e64 v205, v124, 1.0, s[8:9]
	v_cmp_gt_f32_e32 vcc, 1.0, v205
	v_mfma_scale_f32_32x32x64_f8f6f4 v[34:49], v[146:153], v[206:213], v[34:49], v1, v1 op_sel_hi:[0,0,0]
	s_waitcnt vmcnt(3)
	ds_write_b128 v193, v[156:159]
	ds_write_b128 v195, v[160:163] offset:16384
	ds_write_b64 v197, v[172:173] offset:16384
	v_mfma_scale_f32_32x32x64_f8f6f4 v[18:33], v[146:153], v[130:137], v[18:33], v1, v1 op_sel_hi:[0,0,0]
	s_cbranch_vccz .Latt3_c2_698
	s_and_saveexec_b64 s[56:57], s[6:7]
	ds_write_b32 v185, v205 offset:41088
	s_or_b64 exec, exec, s[56:57]
	s_waitcnt lgkmcnt(0)
	v_add_u32_e32 v123, v183, v184
	ds_read_b128 v[124:127], v123 offset:41184
	ds_read_b128 v[130:133], v123 offset:41152
	ds_read_b128 v[134:137], v123 offset:41120
	ds_read_b128 v[138:141], v123 offset:41088
	s_waitcnt lgkmcnt(3)
	v_pk_mul_f32 v[14:15], v[14:15], v[124:125]
	s_waitcnt lgkmcnt(2)
	v_pk_mul_f32 v[10:11], v[10:11], v[130:131]
	s_waitcnt lgkmcnt(1)
	v_pk_mul_f32 v[6:7], v[6:7], v[134:135]
	v_pk_mul_f32 v[16:17], v[16:17], v[126:127]
	v_pk_mul_f32 v[12:13], v[12:13], v[132:133]
	v_pk_mul_f32 v[8:9], v[8:9], v[136:137]
	s_waitcnt lgkmcnt(0)
	v_pk_mul_f32 v[4:5], v[4:5], v[140:141]
	v_pk_mul_f32 v[2:3], v[2:3], v[138:139]
	v_pk_mul_f32 v[62:63], v[62:63], v[124:125]
	v_pk_mul_f32 v[58:59], v[58:59], v[130:131]
	v_pk_mul_f32 v[54:55], v[54:55], v[134:135]
	v_pk_mul_f32 v[64:65], v[64:65], v[126:127]
	v_pk_mul_f32 v[60:61], v[60:61], v[132:133]
	v_pk_mul_f32 v[56:57], v[56:57], v[136:137]
	v_pk_mul_f32 v[52:53], v[52:53], v[140:141]
	v_pk_mul_f32 v[50:51], v[50:51], v[138:139]
	v_pk_mul_f32 v[46:47], v[46:47], v[124:125]
	v_pk_mul_f32 v[42:43], v[42:43], v[130:131]
	v_pk_mul_f32 v[38:39], v[38:39], v[134:135]
	v_pk_mul_f32 v[48:49], v[48:49], v[126:127]
	v_pk_mul_f32 v[44:45], v[44:45], v[132:133]
	v_pk_mul_f32 v[40:41], v[40:41], v[136:137]
	v_pk_mul_f32 v[36:37], v[36:37], v[140:141]
	v_pk_mul_f32 v[34:35], v[34:35], v[138:139]
	v_pk_mul_f32 v[30:31], v[30:31], v[124:125]
	v_pk_mul_f32 v[26:27], v[26:27], v[130:131]
	v_pk_mul_f32 v[22:23], v[22:23], v[134:135]
	v_pk_mul_f32 v[32:33], v[32:33], v[126:127]
	v_pk_mul_f32 v[28:29], v[28:29], v[132:133]
	v_pk_mul_f32 v[24:25], v[24:25], v[136:137]
	v_pk_mul_f32 v[20:21], v[20:21], v[140:141]
	v_pk_mul_f32 v[18:19], v[18:19], v[138:139]
.Latt3_c2_698:
	v_cndmask_b32_e64 v206, v122, v128, s[8:9]
	v_fma_f32 v207, v206, s62, 4.0
	v_fmamk_f32 v122, v82, 0x3dd53b94, v207
	v_fmamk_f32 v123, v83, 0x3dd53b94, v207
	v_fmamk_f32 v124, v84, 0x3dd53b94, v207
	v_fmamk_f32 v125, v85, 0x3dd53b94, v207
	v_fmamk_f32 v126, v86, 0x3dd53b94, v207
	v_fmamk_f32 v127, v87, 0x3dd53b94, v207
	v_fmamk_f32 v128, v88, 0x3dd53b94, v207
	v_fmamk_f32 v129, v89, 0x3dd53b94, v207
	v_fmamk_f32 v130, v90, 0x3dd53b94, v207
	v_fmamk_f32 v131, v91, 0x3dd53b94, v207
	v_fmamk_f32 v132, v92, 0x3dd53b94, v207
	v_fmamk_f32 v133, v93, 0x3dd53b94, v207
	v_fmamk_f32 v134, v94, 0x3dd53b94, v207
	v_fmamk_f32 v95, v95, 0x3dd53b94, v207
	v_fmamk_f32 v96, v96, 0x3dd53b94, v207
	v_fmamk_f32 v97, v97, 0x3dd53b94, v207
	v_exp_f32_e32 v223, v122
	v_exp_f32_e32 v224, v123
	v_exp_f32_e32 v215, v124
	v_exp_f32_e32 v217, v125
	v_exp_f32_e32 v221, v126
	v_exp_f32_e32 v222, v127
	v_exp_f32_e32 v219, v128
	v_exp_f32_e32 v220, v129
	v_exp_f32_e32 v216, v130
	v_exp_f32_e32 v218, v131
	v_exp_f32_e32 v209, v132
	v_exp_f32_e32 v210, v133
	v_exp_f32_e32 v213, v134
	v_exp_f32_e32 v214, v95
	v_exp_f32_e32 v211, v96
	v_exp_f32_e32 v212, v97
	v_fmamk_f32 v82, v66, 0x3dd53b94, v207
	v_fmamk_f32 v83, v67, 0x3dd53b94, v207
	v_fmamk_f32 v84, v68, 0x3dd53b94, v207
	v_fmamk_f32 v85, v69, 0x3dd53b94, v207
	v_fmamk_f32 v86, v70, 0x3dd53b94, v207
	v_fmamk_f32 v87, v71, 0x3dd53b94, v207
	v_fmamk_f32 v88, v72, 0x3dd53b94, v207
	v_fmamk_f32 v89, v73, 0x3dd53b94, v207
	v_fmamk_f32 v90, v74, 0x3dd53b94, v207
	v_fmamk_f32 v91, v75, 0x3dd53b94, v207
	v_fmamk_f32 v92, v76, 0x3dd53b94, v207
	v_fmamk_f32 v93, v77, 0x3dd53b94, v207
	v_fmamk_f32 v94, v78, 0x3dd53b94, v207
	v_fmamk_f32 v95, v79, 0x3dd53b94, v207
	v_fmamk_f32 v96, v80, 0x3dd53b94, v207
	v_fmac_f32_e32 v207, 0x3dd53b94, v81
	s_waitcnt lgkmcnt(0)
	s_barrier
	ds_read_b128 v[66:69], v194 offset:16384
	ds_read_b128 v[74:77], v194 offset:22528
	ds_read_b128 v[70:73], v196 offset:16384
	ds_read_b128 v[78:81], v196 offset:22528
	ds_read_b128 v[146:149], v198 offset:16384
	ds_read_b128 v[138:141], v198 offset:22528
	ds_read_b128 v[150:153], v199 offset:16384
	ds_read_b128 v[142:145], v199 offset:22528
	ds_read_b128 v[130:133], v201 offset:16384
	ds_read_b128 v[122:125], v201 offset:22528
	ds_read_b128 v[134:137], v200 offset:16384
	ds_read_b128 v[126:129], v200 offset:22528
	ds_read_b128 v[244:247], v189 offset:45056
	ds_read_b128 v[248:251], v190 offset:45056
	v_exp_f32_e32 v239, v82
	v_exp_f32_e32 v240, v83
	v_exp_f32_e32 v233, v84
	v_exp_f32_e32 v234, v85
	v_exp_f32_e32 v237, v86
	v_exp_f32_e32 v238, v87
	v_exp_f32_e32 v235, v88
	v_exp_f32_e32 v236, v89
	v_exp_f32_e32 v231, v90
	v_exp_f32_e32 v232, v91
	v_exp_f32_e32 v225, v92
	v_exp_f32_e32 v226, v93
	v_exp_f32_e32 v229, v94
	v_exp_f32_e32 v230, v95
	v_exp_f32_e32 v227, v96
	v_exp_f32_e32 v228, v207
	s_cmpk_gt_u32 s73, 0x80
	s_cselect_b64 s[56:57], -1, 0
	s_and_b64 vcc, exec, s[56:57]
	s_cbranch_vccnz .Latt3_c2_700
	buffer_load_dwordx4 v[156:159], v191, s[40:43], s11 offen
	buffer_load_dwordx4 v[160:163], v191, s[36:39], s72 offen
	buffer_load_dwordx2 v[172:173], v192, s[36:39], s72 offen
.Latt3_c2_700:
	s_waitcnt lgkmcnt(11)
	v_mfma_scale_f32_32x32x64_f8f6f4 v[82:97], v[66:73], v[114:121], 0, v1, v1 op_sel_hi:[0,0,0]
	v_add_f32_e32 v241, 0, v223
	v_add_f32_e32 v241, v224, v241
	v_add_f32_e32 v241, v215, v241
	v_add_f32_e32 v241, v217, v241
	v_add_f32_e32 v241, v221, v241
	v_add_f32_e32 v241, v222, v241
	v_add_f32_e32 v241, v219, v241
	v_add_f32_e32 v241, v220, v241
	s_waitcnt lgkmcnt(10)
	v_mfma_scale_f32_32x32x64_f8f6f4 v[66:81], v[74:81], v[114:121], 0, v1, v1 op_sel_hi:[0,0,0]
	v_add_f32_e32 v241, v216, v241
	v_add_f32_e32 v241, v218, v241
	v_add_f32_e32 v241, v209, v241
	v_add_f32_e32 v241, v210, v241
	v_add_f32_e32 v241, v213, v241
	v_add_f32_e32 v241, v214, v241
	v_add_f32_e32 v241, v211, v241
	v_add_f32_e32 v241, v212, v241
	s_waitcnt lgkmcnt(7)
	v_mfma_scale_f32_32x32x64_f8f6f4 v[82:97], v[146:153], v[106:113], v[82:97], v1, v1 op_sel_hi:[0,0,0]
	v_add_f32_e32 v241, v239, v241
	v_add_f32_e32 v241, v240, v241
	v_add_f32_e32 v241, v233, v241
	v_add_f32_e32 v241, v234, v241
	v_add_f32_e32 v241, v237, v241
	v_add_f32_e32 v241, v238, v241
	v_add_f32_e32 v241, v235, v241
	v_add_f32_e32 v241, v236, v241
	s_waitcnt lgkmcnt(6)
	v_mfma_scale_f32_32x32x64_f8f6f4 v[66:81], v[138:145], v[106:113], v[66:81], v1, v1 op_sel_hi:[0,0,0]
	v_add_f32_e32 v241, v231, v241
	v_add_f32_e32 v241, v232, v241
	v_add_f32_e32 v241, v225, v241
	v_add_f32_e32 v241, v226, v241
	v_add_f32_e32 v241, v229, v241
	v_add_f32_e32 v241, v230, v241
	v_add_f32_e32 v241, v227, v241
	v_add_f32_e32 v207, v228, v241
	v_mov_b32_e32 v208, v207
	s_nop 1
	v_permlane32_swap_b32_e32 v207, v208
	v_cvt_pk_fp8_f32 v138, v223, v224
	v_cvt_pk_fp8_f32 v142, v239, v240
	v_cvt_pk_fp8_f32 v139, v221, v222
	v_cvt_pk_fp8_f32 v143, v237, v238
	v_cvt_pk_fp8_f32 v140, v216, v218
	v_cvt_pk_fp8_f32 v144, v231, v232
	v_cvt_pk_fp8_f32 v141, v213, v214
	s_waitcnt lgkmcnt(3)
	v_mfma_scale_f32_32x32x64_f8f6f4 v[82:97], v[130:137], v[98:105], v[82:97], v1, v1 op_sel_hi:[0,0,0]
	v_cvt_pk_fp8_f32 v145, v229, v230
	v_cvt_pk_fp8_f32 v138, v215, v217 op_sel:[0,0,1]
	v_cvt_pk_fp8_f32 v142, v233, v234 op_sel:[0,0,1]
	v_cvt_pk_fp8_f32 v139, v219, v220 op_sel:[0,0,1]
	v_cvt_pk_fp8_f32 v143, v235, v236 op_sel:[0,0,1]
	v_cvt_pk_fp8_f32 v140, v209, v210 op_sel:[0,0,1]
	v_cvt_pk_fp8_f32 v144, v225, v226 op_sel:[0,0,1]
	v_cvt_pk_fp8_f32 v141, v211, v212 op_sel:[0,0,1]
	v_cvt_pk_fp8_f32 v145, v227, v228 op_sel:[0,0,1]
	s_waitcnt lgkmcnt(2)
	v_mfma_scale_f32_32x32x64_f8f6f4 v[66:81], v[122:129], v[98:105], v[66:81], v1, v1 op_sel_hi:[0,0,0]
	ds_read_b128 v[130:133], v187 offset:47104
	ds_read_b128 v[146:149], v187 offset:49152
	ds_read_b128 v[134:137], v186 offset:47104
	ds_read_b128 v[210:213], v187 offset:51200
	ds_read_b128 v[150:153], v186 offset:49152
	ds_read_b128 v[214:217], v186 offset:51200
	s_waitcnt lgkmcnt(6)
	v_mfma_scale_f32_32x32x64_f8f6f4 v[2:17], v[138:145], v[244:251], v[2:17], v1, v1 op_sel_hi:[0,0,0]
	s_nop 1
	v_max_f32_e32 v122, v83, v83
	v_max_f32_e32 v123, v82, v82
	v_max_f32_e32 v122, v123, v122
	v_max3_f32 v122, v122, v84, v85
	v_max3_f32 v122, v122, v86, v87
	v_max3_f32 v122, v122, v88, v89
	v_max3_f32 v122, v122, v90, v91
	v_max3_f32 v122, v122, v92, v93
	v_max3_f32 v122, v122, v94, v95
	v_max3_f32 v122, v122, v96, v97
	v_max3_f32 v122, v122, v66, v67
	v_max3_f32 v122, v122, v68, v69
	v_max3_f32 v122, v122, v70, v71
	v_max3_f32 v122, v122, v72, v73
	v_max3_f32 v122, v122, v74, v75
	s_waitcnt lgkmcnt(3)
	v_mfma_scale_f32_32x32x64_f8f6f4 v[50:65], v[138:145], v[130:137], v[50:65], v1, v1 op_sel_hi:[0,0,0]
	v_max3_f32 v122, v122, v76, v77
	v_max3_f32 v122, v122, v78, v79
	v_max3_f32 v122, v122, v80, v81
	v_mov_b32_e32 v123, v122
	s_nop 1
	v_permlane32_swap_b32_e32 v122, v123
	v_max_f32_e32 v123, v123, v123
	v_max_f32_e32 v122, v122, v122
	v_max_f32_e32 v122, v122, v123
	v_max_f32_e32 v124, v206, v206
	v_sub_f32_e32 v123, v122, v206
	v_max_f32_e32 v122, v124, v122
	v_sub_f32_e32 v124, v206, v122
	v_mul_f32_e32 v124, 0x3dd53b94, v124
	v_exp_f32_e32 v124, v124
	s_waitcnt lgkmcnt(0)
	v_mfma_scale_f32_32x32x64_f8f6f4 v[34:49], v[138:145], v[146:153], v[34:49], v1, v1 op_sel_hi:[0,0,0]
	v_cmp_ge_f32_e32 vcc, s61, v123
	s_cmp_eq_u64 vcc, exec
	s_cselect_b64 s[8:9], -1, 0
	s_waitcnt vmcnt(3)
	v_cndmask_b32_e64 v129, v124, 1.0, s[8:9]
	v_cmp_gt_f32_e32 vcc, 1.0, v129
	s_waitcnt vmcnt(2)
	ds_write_b128 v193, v[164:167] offset:8192
	s_waitcnt vmcnt(1)
	ds_write_b128 v195, v[168:171] offset:28672
	s_waitcnt vmcnt(0)
	ds_write_b64 v197, v[174:175] offset:28672
	v_mfma_scale_f32_32x32x64_f8f6f4 v[18:33], v[138:145], v[210:217], v[18:33], v1, v1 op_sel_hi:[0,0,0]
	s_cbranch_vccz .Latt3_c2_704
	s_and_saveexec_b64 s[58:59], s[6:7]
	ds_write_b32 v185, v129 offset:41088
	s_or_b64 exec, exec, s[58:59]
	s_waitcnt lgkmcnt(0)
	v_add_u32_e32 v123, v183, v184
	ds_read_b128 v[124:127], v123 offset:41184
	ds_read_b128 v[130:133], v123 offset:41152
	ds_read_b128 v[134:137], v123 offset:41120
	ds_read_b128 v[138:141], v123 offset:41088
	s_waitcnt lgkmcnt(3)
	v_pk_mul_f32 v[14:15], v[14:15], v[124:125]
	s_waitcnt lgkmcnt(2)
	v_pk_mul_f32 v[10:11], v[10:11], v[130:131]
	s_waitcnt lgkmcnt(1)
	v_pk_mul_f32 v[6:7], v[6:7], v[134:135]
	v_pk_mul_f32 v[16:17], v[16:17], v[126:127]
	v_pk_mul_f32 v[12:13], v[12:13], v[132:133]
	v_pk_mul_f32 v[8:9], v[8:9], v[136:137]
	s_waitcnt lgkmcnt(0)
	v_pk_mul_f32 v[4:5], v[4:5], v[140:141]
	v_pk_mul_f32 v[2:3], v[2:3], v[138:139]
	v_pk_mul_f32 v[62:63], v[62:63], v[124:125]
	v_pk_mul_f32 v[58:59], v[58:59], v[130:131]
	v_pk_mul_f32 v[54:55], v[54:55], v[134:135]
	v_pk_mul_f32 v[64:65], v[64:65], v[126:127]
	v_pk_mul_f32 v[60:61], v[60:61], v[132:133]
	v_pk_mul_f32 v[56:57], v[56:57], v[136:137]
	v_pk_mul_f32 v[52:53], v[52:53], v[140:141]
	v_pk_mul_f32 v[50:51], v[50:51], v[138:139]
	v_pk_mul_f32 v[46:47], v[46:47], v[124:125]
	v_pk_mul_f32 v[42:43], v[42:43], v[130:131]
	v_pk_mul_f32 v[38:39], v[38:39], v[134:135]
	v_pk_mul_f32 v[48:49], v[48:49], v[126:127]
	v_pk_mul_f32 v[44:45], v[44:45], v[132:133]
	v_pk_mul_f32 v[40:41], v[40:41], v[136:137]
	v_pk_mul_f32 v[36:37], v[36:37], v[140:141]
	v_pk_mul_f32 v[34:35], v[34:35], v[138:139]
	v_pk_mul_f32 v[30:31], v[30:31], v[124:125]
	v_pk_mul_f32 v[26:27], v[26:27], v[130:131]
	v_pk_mul_f32 v[22:23], v[22:23], v[134:135]
	v_pk_mul_f32 v[32:33], v[32:33], v[126:127]
	v_pk_mul_f32 v[28:29], v[28:29], v[132:133]
	v_pk_mul_f32 v[24:25], v[24:25], v[136:137]
	v_pk_mul_f32 v[20:21], v[20:21], v[140:141]
	v_pk_mul_f32 v[18:19], v[18:19], v[138:139]

.LBB0_706:
	ds_read_b128 v[80:83], v196 offset:28672
	ds_read_b128 v[76:79], v194 offset:28672
	ds_read_b128 v[146:149], v194 offset:34816
	ds_read_b128 v[150:153], v196 offset:34816
	ds_read_b128 v[156:159], v198 offset:28672
	ds_read_b128 v[164:167], v198 offset:34816
	ds_read_b128 v[160:163], v199 offset:28672
	ds_read_b128 v[168:171], v199 offset:34816
	ds_read_b128 v[192:195], v201 offset:28672
	ds_read_b128 v[202:205], v201 offset:34816
	s_waitcnt lgkmcnt(8)
	v_mfma_scale_f32_32x32x64_f8f6f4 v[82:97], v[76:83], v[114:121], 0, v1, v1 op_sel_hi:[0,0,0]
	ds_read_b128 v[196:199], v200 offset:28672
	ds_read_b128 v[206:209], v200 offset:34816
	v_exp_f32_e32 v172, v70
	v_exp_f32_e32 v173, v71
	v_exp_f32_e32 v174, v68
	v_exp_f32_e32 v175, v69
	v_exp_f32_e32 v191, v66
	v_exp_f32_e32 v200, v67
	v_exp_f32_e32 v201, v74
	v_exp_f32_e32 v210, v75
	v_exp_f32_e32 v211, v72
	v_exp_f32_e32 v212, v73
	v_exp_f32_e32 v124, v124
	v_exp_f32_e32 v125, v125
	v_exp_f32_e32 v122, v122
	v_exp_f32_e32 v123, v123
	s_waitcnt lgkmcnt(8)
	v_mfma_scale_f32_32x32x64_f8f6f4 v[66:81], v[146:153], v[114:121], 0, v1, v1 op_sel_hi:[0,0,0]
	v_add_f32_e32 v114, 0, v144
	v_add_f32_e32 v114, v145, v114
	v_add_f32_e32 v114, v136, v114
	v_add_f32_e32 v114, v138, v114
	v_add_f32_e32 v114, v142, v114
	v_add_f32_e32 v114, v143, v114
	v_add_f32_e32 v114, v140, v114
	v_add_f32_e32 v114, v141, v114
	v_add_f32_e32 v114, v137, v114
	v_add_f32_e32 v114, v139, v114
	v_add_f32_e32 v114, v130, v114
	v_add_f32_e32 v114, v131, v114
	v_add_f32_e32 v114, v134, v114
	v_add_f32_e32 v114, v135, v114
	v_add_f32_e32 v114, v132, v114
	s_waitcnt lgkmcnt(5)
	v_mfma_scale_f32_32x32x64_f8f6f4 v[82:97], v[156:163], v[106:113], v[82:97], v1, v1 op_sel_hi:[0,0,0]
	v_add_f32_e32 v114, v133, v114
	v_add_f32_e32 v114, v124, v114
	v_add_f32_e32 v114, v125, v114
	v_add_f32_e32 v114, v122, v114
	v_add_f32_e32 v114, v123, v114
	v_add_f32_e32 v114, v172, v114
	v_add_f32_e32 v114, v173, v114
	v_add_f32_e32 v114, v174, v114
	v_add_f32_e32 v114, v175, v114
	v_add_f32_e32 v114, v191, v114
	v_add_f32_e32 v114, v200, v114
	v_exp_f32_e32 v116, v126
	v_add_f32_e32 v114, v201, v114
	v_exp_f32_e32 v117, v127
	v_add_f32_e32 v114, v210, v114
	s_waitcnt lgkmcnt(4)
	v_mfma_scale_f32_32x32x64_f8f6f4 v[66:81], v[164:171], v[106:113], v[66:81], v1, v1 op_sel_hi:[0,0,0]
	v_add_f32_e32 v106, v211, v114
	v_add_f32_e32 v106, v212, v106
	v_mov_b32_e32 v108, v155
	v_mov_b32_e32 v112, v155
	v_mov_b32_e32 v109, v155
	v_mov_b32_e32 v113, v155
	v_mov_b32_e32 v110, v155
	v_mov_b32_e32 v114, v155
	v_mov_b32_e32 v111, v155
	v_mov_b32_e32 v115, v155
	v_add_f32_e32 v106, v116, v106
	v_cvt_pk_fp8_f32 v108, v144, v145
	v_cvt_pk_fp8_f32 v112, v124, v125
	v_cvt_pk_fp8_f32 v109, v142, v143
	v_cvt_pk_fp8_f32 v113, v172, v173
	s_waitcnt lgkmcnt(1)
	v_mfma_scale_f32_32x32x64_f8f6f4 v[82:97], v[192:199], v[98:105], v[82:97], v1, v1 op_sel_hi:[0,0,0]
	v_cvt_pk_fp8_f32 v110, v137, v139
	v_cvt_pk_fp8_f32 v114, v191, v200
	v_cvt_pk_fp8_f32 v111, v134, v135
	v_cvt_pk_fp8_f32 v115, v211, v212
	v_add_f32_e32 v106, v117, v106
	v_mov_b32_e32 v107, v106
	s_nop 1
	v_permlane32_swap_b32_e32 v106, v107
	v_cvt_pk_fp8_f32 v108, v136, v138 op_sel:[0,0,1]
	v_cvt_pk_fp8_f32 v112, v122, v123 op_sel:[0,0,1]
	v_cvt_pk_fp8_f32 v109, v140, v141 op_sel:[0,0,1]
	v_cvt_pk_fp8_f32 v113, v174, v175 op_sel:[0,0,1]
	v_cvt_pk_fp8_f32 v110, v130, v131 op_sel:[0,0,1]
	v_cvt_pk_fp8_f32 v114, v201, v210 op_sel:[0,0,1]
	v_cvt_pk_fp8_f32 v111, v132, v133 op_sel:[0,0,1]
	s_waitcnt lgkmcnt(0)
	v_mfma_scale_f32_32x32x64_f8f6f4 v[66:81], v[202:209], v[98:105], v[66:81], v1, v1 op_sel_hi:[0,0,0]
	v_cvt_pk_fp8_f32 v115, v116, v117 op_sel:[0,0,1]
	ds_read_b128 v[98:101], v189 offset:8192
	ds_read_b128 v[102:105], v190 offset:8192
	v_max_f32_e32 v124, v83, v83
	v_max_f32_e32 v125, v82, v82
	v_max_f32_e32 v124, v125, v124
	v_max3_f32 v124, v124, v84, v85
	v_max3_f32 v124, v124, v86, v87
	v_max3_f32 v124, v124, v88, v89
	s_waitcnt lgkmcnt(0)
	v_mfma_scale_f32_32x32x64_f8f6f4 v[2:17], v[108:115], v[98:105], v[2:17], v1, v1 op_sel_hi:[0,0,0]
	ds_read_b128 v[98:101], v187 offset:10240
	ds_read_b128 v[116:119], v187 offset:12288
	ds_read_b128 v[102:105], v186 offset:10240
	ds_read_b128 v[130:133], v187 offset:14336
	ds_read_b128 v[120:123], v186 offset:12288
	ds_read_b128 v[134:137], v186 offset:14336
	v_max3_f32 v124, v124, v90, v91
	v_max3_f32 v124, v124, v92, v93
	s_waitcnt lgkmcnt(0)
	s_barrier
	v_mfma_scale_f32_32x32x64_f8f6f4 v[50:65], v[108:115], v[98:105], v[50:65], v1, v1 op_sel_hi:[0,0,0]
	v_max3_f32 v98, v124, v94, v95
	v_max3_f32 v98, v98, v96, v97
	v_max3_f32 v98, v98, v66, v67
	v_max3_f32 v98, v98, v68, v69
	v_max3_f32 v98, v98, v70, v71
	v_max3_f32 v98, v98, v72, v73
	v_max3_f32 v98, v98, v74, v75
	v_max3_f32 v98, v98, v76, v77
	v_max3_f32 v98, v98, v78, v79
	v_max3_f32 v98, v98, v80, v81
	v_mov_b32_e32 v99, v98
	s_nop 1
	v_permlane32_swap_b32_e32 v98, v99
	v_max_f32_e32 v99, v99, v99
	v_max_f32_e32 v98, v98, v98
	v_mfma_scale_f32_32x32x64_f8f6f4 v[34:49], v[108:115], v[116:123], v[34:49], v1, v1 op_sel_hi:[0,0,0]
	v_max_f32_e32 v98, v98, v99
	v_max_f32_e32 v99, v128, v128
	v_max_f32_e32 v99, v99, v98
	v_sub_f32_e32 v100, v98, v128
	v_sub_f32_e32 v98, v128, v99
	v_mul_f32_e32 v98, 0x3dd53b94, v98
	v_exp_f32_e32 v98, v98
	v_cmp_ge_f32_e32 vcc, s61, v100
	s_cmp_eq_u64 vcc, exec
	s_cselect_b64 s[8:9], -1, 0
	v_cndmask_b32_e64 v98, v98, 1.0, s[8:9]
	v_cmp_gt_f32_e32 vcc, 1.0, v98
	v_mfma_scale_f32_32x32x64_f8f6f4 v[18:33], v[108:115], v[130:137], v[18:33], v1, v1 op_sel_hi:[0,0,0]
	s_cbranch_vccz .LBB0_710
	s_and_saveexec_b64 s[36:37], s[6:7]
	ds_write_b32 v185, v98 offset:41088
	s_or_b64 exec, exec, s[36:37]
	s_waitcnt lgkmcnt(0)
	v_add_u32_e32 v104, v183, v184
	ds_read_b128 v[100:103], v104 offset:41184
	ds_read_b128 v[108:111], v104 offset:41152
	ds_read_b128 v[112:115], v104 offset:41120
	ds_read_b128 v[116:119], v104 offset:41088
	s_waitcnt lgkmcnt(3)
	v_pk_mul_f32 v[14:15], v[14:15], v[100:101]
	s_waitcnt lgkmcnt(2)
	v_pk_mul_f32 v[10:11], v[10:11], v[108:109]
	s_waitcnt lgkmcnt(1)
	v_pk_mul_f32 v[6:7], v[6:7], v[112:113]
	v_pk_mul_f32 v[16:17], v[16:17], v[102:103]
	v_pk_mul_f32 v[12:13], v[12:13], v[110:111]
	v_pk_mul_f32 v[8:9], v[8:9], v[114:115]
	s_waitcnt lgkmcnt(0)
	v_pk_mul_f32 v[4:5], v[4:5], v[118:119]
	v_pk_mul_f32 v[2:3], v[2:3], v[116:117]
	v_pk_mul_f32 v[62:63], v[62:63], v[100:101]
	v_pk_mul_f32 v[58:59], v[58:59], v[108:109]
	v_pk_mul_f32 v[54:55], v[54:55], v[112:113]
	v_pk_mul_f32 v[64:65], v[64:65], v[102:103]
	v_pk_mul_f32 v[60:61], v[60:61], v[110:111]
	v_pk_mul_f32 v[56:57], v[56:57], v[114:115]
	v_pk_mul_f32 v[52:53], v[52:53], v[118:119]
	v_pk_mul_f32 v[50:51], v[50:51], v[116:117]
	v_pk_mul_f32 v[46:47], v[46:47], v[100:101]
	v_pk_mul_f32 v[42:43], v[42:43], v[108:109]
	v_pk_mul_f32 v[38:39], v[38:39], v[112:113]
	v_pk_mul_f32 v[48:49], v[48:49], v[102:103]
	v_pk_mul_f32 v[44:45], v[44:45], v[110:111]
	v_pk_mul_f32 v[40:41], v[40:41], v[114:115]
	v_pk_mul_f32 v[36:37], v[36:37], v[118:119]
	v_pk_mul_f32 v[34:35], v[34:35], v[116:117]
	v_pk_mul_f32 v[30:31], v[30:31], v[100:101]
	v_pk_mul_f32 v[26:27], v[26:27], v[108:109]
	v_pk_mul_f32 v[22:23], v[22:23], v[112:113]
	v_pk_mul_f32 v[32:33], v[32:33], v[102:103]
	v_pk_mul_f32 v[28:29], v[28:29], v[110:111]
	v_pk_mul_f32 v[24:25], v[24:25], v[114:115]
	v_pk_mul_f32 v[20:21], v[20:21], v[118:119]
	v_pk_mul_f32 v[18:19], v[18:19], v[116:117]
.LBB0_710:
	v_cndmask_b32_e64 v99, v99, v128, s[8:9]
	v_fma_f32 v119, v99, s62, 4.0
	v_fmamk_f32 v82, v82, 0x3dd53b94, v119
	v_fmamk_f32 v83, v83, 0x3dd53b94, v119
	v_exp_f32_e32 v118, v82
	v_fmamk_f32 v84, v84, 0x3dd53b94, v119
	v_exp_f32_e32 v120, v83
	v_fmamk_f32 v85, v85, 0x3dd53b94, v119
	v_exp_f32_e32 v105, v84
	v_fmamk_f32 v86, v86, 0x3dd53b94, v119
	v_fmamk_f32 v66, v66, 0x3dd53b94, v119
	v_exp_f32_e32 v109, v85
	v_fmamk_f32 v87, v87, 0x3dd53b94, v119
	v_exp_f32_e32 v113, v86
	v_exp_f32_e32 v132, v66
	v_add_f32_e32 v66, 0, v118
	v_fmamk_f32 v88, v88, 0x3dd53b94, v119
	v_exp_f32_e32 v114, v87
	v_add_f32_e32 v66, v120, v66
	v_fmamk_f32 v89, v89, 0x3dd53b94, v119
	v_exp_f32_e32 v111, v88
	v_add_f32_e32 v66, v105, v66
	v_fmamk_f32 v90, v90, 0x3dd53b94, v119
	v_exp_f32_e32 v112, v89
	v_add_f32_e32 v66, v109, v66
	v_fmamk_f32 v91, v91, 0x3dd53b94, v119
	v_exp_f32_e32 v108, v90
	v_add_f32_e32 v66, v113, v66
	v_fmamk_f32 v92, v92, 0x3dd53b94, v119
	v_exp_f32_e32 v110, v91
	v_add_f32_e32 v66, v114, v66
	v_fmamk_f32 v93, v93, 0x3dd53b94, v119
	v_exp_f32_e32 v99, v92
	v_add_f32_e32 v66, v111, v66
	v_fmamk_f32 v94, v94, 0x3dd53b94, v119
	v_exp_f32_e32 v100, v93
	v_add_f32_e32 v66, v112, v66
	v_fmamk_f32 v95, v95, 0x3dd53b94, v119
	v_exp_f32_e32 v103, v94
	v_add_f32_e32 v66, v108, v66
	v_fmamk_f32 v96, v96, 0x3dd53b94, v119
	v_exp_f32_e32 v104, v95
	v_add_f32_e32 v66, v110, v66
	v_fmamk_f32 v97, v97, 0x3dd53b94, v119
	v_exp_f32_e32 v101, v96
	v_add_f32_e32 v66, v99, v66
	v_exp_f32_e32 v102, v97
	v_add_f32_e32 v66, v100, v66
	v_fmamk_f32 v67, v67, 0x3dd53b94, v119
	v_add_f32_e32 v66, v103, v66
	v_fmamk_f32 v68, v68, 0x3dd53b94, v119
	v_exp_f32_e32 v133, v67
	v_add_f32_e32 v66, v104, v66
	v_fmamk_f32 v69, v69, 0x3dd53b94, v119
	v_exp_f32_e32 v125, v68
	v_add_f32_e32 v66, v101, v66
	v_fmamk_f32 v70, v70, 0x3dd53b94, v119
	v_exp_f32_e32 v126, v69
	v_add_f32_e32 v66, v102, v66
	v_fmamk_f32 v71, v71, 0x3dd53b94, v119
	v_exp_f32_e32 v130, v70
	v_add_f32_e32 v66, v132, v66
	v_fmamk_f32 v72, v72, 0x3dd53b94, v119
	v_exp_f32_e32 v131, v71
	v_add_f32_e32 v66, v133, v66
	v_fmamk_f32 v73, v73, 0x3dd53b94, v119
	v_exp_f32_e32 v127, v72
	v_add_f32_e32 v66, v125, v66
	v_fmamk_f32 v74, v74, 0x3dd53b94, v119
	v_exp_f32_e32 v128, v73
	v_add_f32_e32 v66, v126, v66
	v_fmamk_f32 v75, v75, 0x3dd53b94, v119
	v_exp_f32_e32 v123, v74
	v_add_f32_e32 v66, v130, v66
	v_fmamk_f32 v76, v76, 0x3dd53b94, v119
	v_exp_f32_e32 v124, v75
	v_add_f32_e32 v66, v131, v66
	v_fmamk_f32 v77, v77, 0x3dd53b94, v119
	v_exp_f32_e32 v115, v76
	v_add_f32_e32 v66, v127, v66
	v_fmamk_f32 v78, v78, 0x3dd53b94, v119
	v_exp_f32_e32 v116, v77
	v_add_f32_e32 v66, v128, v66
	v_fmamk_f32 v79, v79, 0x3dd53b94, v119
	v_exp_f32_e32 v121, v78
	v_add_f32_e32 v66, v123, v66
	v_fmamk_f32 v80, v80, 0x3dd53b94, v119
	v_exp_f32_e32 v122, v79
	v_add_f32_e32 v66, v124, v66
	v_fmac_f32_e32 v119, 0x3dd53b94, v81
	v_exp_f32_e32 v117, v80
	v_add_f32_e32 v66, v115, v66
	v_exp_f32_e32 v119, v119
	v_add_f32_e32 v66, v116, v66
	v_add_f32_e32 v66, v121, v66
	v_add_f32_e32 v66, v122, v66
	v_add_f32_e32 v66, v117, v66
	v_add_f32_e32 v134, v119, v66
	v_mov_b32_e32 v135, v134
	s_nop 1
	v_permlane32_swap_b32_e32 v134, v135
	ds_read_b128 v[90:93], v189 offset:45056
	ds_read_b128 v[94:97], v190 offset:45056
	ds_read_b128 v[82:85], v187 offset:47104
	ds_read_b128 v[74:77], v187 offset:49152
	ds_read_b128 v[86:89], v186 offset:47104
	ds_read_b128 v[66:69], v187 offset:51200
	ds_read_b128 v[78:81], v186 offset:49152
	ds_read_b128 v[70:73], v186 offset:51200
	s_and_saveexec_b64 s[8:9], s[6:7]
	s_cbranch_execz .LBB0_692
	v_add_f32_e32 v106, v106, v107
	v_fmac_f32_e32 v106, v188, v129
	v_add_f32_e32 v107, v134, v135
	v_fmac_f32_e32 v107, v106, v98
	ds_write_b32 v185, v107 offset:40960
	s_branch .LBB0_692
